# gate phase: prefetch w_s/VgT/UZ tiles at item top, A-build unrolled from registers
# baseline (speedup 1.0000x reference)
.LBB0_190:
	s_ashr_i32 s12, s42, 4
	s_and_b32 s16, s42, 7
	s_and_b32 s17, s12, 0x7ffffff8
	s_or_b32 s16, s17, s16
	s_lshl_b32 s16, s16, 1
	s_bfe_u32 s17, s42, 0x10006
	s_or_b32 s16, s16, s17
	s_lshl_b32 s18, s42, 4
	s_and_b32 s18, s18, 0x380
	v_add_u32_e32 v248, s18, v148
	v_ashrrev_i32_e32 v249, 31, v248
	v_lshlrev_b64 v[248:249], 9, v[248:249]
	v_lshl_add_u64 v[248:249], v[164:165], 0, v[248:249]
	global_load_dwordx4 v[96:99], v[248:249], off
	global_load_dwordx4 v[100:103], v[248:249], off offset:16
	global_load_dwordx4 v[104:107], v[248:249], off offset:32
	global_load_dwordx4 v[108:111], v[248:249], off offset:48
	global_load_dwordx4 v[112:115], v[248:249], off offset:64
	global_load_dwordx4 v[116:119], v[248:249], off offset:80
	global_load_dwordx4 v[120:123], v[248:249], off offset:96
	global_load_dwordx4 v[124:127], v[248:249], off offset:112
	s_lshr_b32 s19, s42, 3
	s_and_b32 s19, s19, 7
	s_lshl_b32 s18, s16, 11
	s_lshl_b32 s22, s19, 8
	s_or_b32 s18, s18, s22
	v_ashrrev_i32_e32 v250, 4, v153
	v_add_u32_e32 v250, s18, v250
	v_mov_b32_e32 v251, 0
	v_lshlrev_b64 v[250:251], 8, v[250:251]
	v_lshl_add_u64 v[250:251], v[150:151], 0, v[250:251]
	s_movk_i32 s22, 0x2000
	s_mov_b32 s23, 0
	global_load_dwordx4 v[64:67], v[250:251], off
	v_lshl_add_u64 v[250:251], v[250:251], 0, s[22:23]
	global_load_dwordx4 v[68:71], v[250:251], off
	v_lshl_add_u64 v[250:251], v[250:251], 0, s[22:23]
	global_load_dwordx4 v[72:75], v[250:251], off
	v_lshl_add_u64 v[250:251], v[250:251], 0, s[22:23]
	global_load_dwordx4 v[76:79], v[250:251], off
	v_lshl_add_u64 v[250:251], v[250:251], 0, s[22:23]
	global_load_dwordx4 v[80:83], v[250:251], off
	v_lshl_add_u64 v[250:251], v[250:251], 0, s[22:23]
	global_load_dwordx4 v[84:87], v[250:251], off
	v_lshl_add_u64 v[250:251], v[250:251], 0, s[22:23]
	global_load_dwordx4 v[88:91], v[250:251], off
	v_lshl_add_u64 v[250:251], v[250:251], 0, s[22:23]
	global_load_dwordx4 v[92:95], v[250:251], off
	v_lshl_add_u32 v248, s16, 7, v178
	v_ashrrev_i32_e32 v249, 31, v248
	v_lshlrev_b64 v[248:249], 12, v[248:249]
	v_lshl_or_b32 v248, s19, 9, v248
	v_lshl_add_u64 v[248:249], v[166:167], 0, v[248:249]
	s_mov_b32 s22, 0x6000000
	v_lshl_add_u64 v[248:249], v[248:249], 0, s[22:23]
	s_mov_b32 s22, 0x8000
	global_load_dwordx4 v[216:219], v[248:249], off
	v_lshl_add_u64 v[248:249], v[248:249], 0, s[22:23]
	global_load_dwordx4 v[220:223], v[248:249], off
	v_lshl_add_u64 v[248:249], v[248:249], 0, s[22:23]
	global_load_dwordx4 v[224:227], v[248:249], off
	v_lshl_add_u64 v[248:249], v[248:249], 0, s[22:23]
	global_load_dwordx4 v[228:231], v[248:249], off
	v_lshl_add_u64 v[248:249], v[248:249], 0, s[22:23]
	global_load_dwordx4 v[232:235], v[248:249], off
	v_lshl_add_u64 v[248:249], v[248:249], 0, s[22:23]
	global_load_dwordx4 v[236:239], v[248:249], off
	v_lshl_add_u64 v[248:249], v[248:249], 0, s[22:23]
	global_load_dwordx4 v[240:243], v[248:249], off
	v_lshl_add_u64 v[248:249], v[248:249], 0, s[22:23]
	global_load_dwordx4 v[244:247], v[248:249], off
	s_waitcnt lgkmcnt(0)
	s_barrier
	s_and_saveexec_b64 s[18:19], s[4:5]
	s_cbranch_execz .LBB0_192
	v_lshl_add_u32 v0, s16, 7, v153
	v_ashrrev_i32_e32 v1, 31, v0
	v_lshlrev_b64 v[0:1], 8, v[0:1]
	v_lshl_add_u64 v[60:61], s[10:11], 0, v[0:1]
	global_load_dwordx4 v[0:3], v[60:61], off
	global_load_dwordx4 v[4:7], v[60:61], off offset:16
	global_load_dwordx4 v[8:11], v[60:61], off offset:32
	global_load_dwordx4 v[12:15], v[60:61], off offset:48
	global_load_dwordx4 v[16:19], v[60:61], off offset:64
	global_load_dwordx4 v[20:23], v[60:61], off offset:80
	global_load_dwordx4 v[24:27], v[60:61], off offset:96
	global_load_dwordx4 v[28:31], v[60:61], off offset:112
	global_load_dwordx4 v[32:35], v[60:61], off offset:128
	global_load_dwordx4 v[36:39], v[60:61], off offset:144
	global_load_dwordx4 v[40:43], v[60:61], off offset:160
	global_load_dwordx4 v[44:47], v[60:61], off offset:176
	global_load_dwordx4 v[48:51], v[60:61], off offset:192
	global_load_dwordx4 v[52:55], v[60:61], off offset:208
	global_load_dwordx4 v[56:59], v[60:61], off offset:224
	s_nop 0
	global_load_dwordx4 v[60:63], v[60:61], off offset:240
	s_waitcnt vmcnt(15)
	v_pk_add_f32 v[0:1], v[0:1], 0 op_sel_hi:[1,0]
	s_nop 0
	v_pk_add_f32 v[0:1], v[0:1], v[2:3]
	s_waitcnt vmcnt(14)
	v_pk_add_f32 v[0:1], v[0:1], v[4:5]
	s_nop 0
	v_pk_add_f32 v[0:1], v[0:1], v[6:7]
	s_waitcnt vmcnt(13)
	v_pk_add_f32 v[0:1], v[0:1], v[8:9]
	s_nop 0
	v_pk_add_f32 v[0:1], v[0:1], v[10:11]
	s_waitcnt vmcnt(12)
	v_pk_add_f32 v[0:1], v[0:1], v[12:13]
	s_nop 0
	v_pk_add_f32 v[0:1], v[0:1], v[14:15]
	s_waitcnt vmcnt(11)
	v_pk_add_f32 v[0:1], v[0:1], v[16:17]
	s_nop 0
	v_pk_add_f32 v[0:1], v[0:1], v[18:19]
	s_waitcnt vmcnt(10)
	v_pk_add_f32 v[0:1], v[0:1], v[20:21]
	s_nop 0
	v_pk_add_f32 v[0:1], v[0:1], v[22:23]
	s_waitcnt vmcnt(9)
	v_pk_add_f32 v[0:1], v[0:1], v[24:25]
	s_nop 0
	v_pk_add_f32 v[0:1], v[0:1], v[26:27]
	s_waitcnt vmcnt(8)
	v_pk_add_f32 v[0:1], v[0:1], v[28:29]
	s_nop 0
	v_pk_add_f32 v[0:1], v[0:1], v[30:31]
	s_waitcnt vmcnt(7)
	v_pk_add_f32 v[0:1], v[0:1], v[32:33]
	s_nop 0
	v_pk_add_f32 v[0:1], v[0:1], v[34:35]
	s_waitcnt vmcnt(6)
	v_pk_add_f32 v[0:1], v[0:1], v[36:37]
	s_nop 0
	v_pk_add_f32 v[0:1], v[0:1], v[38:39]
	s_waitcnt vmcnt(5)
	v_pk_add_f32 v[0:1], v[0:1], v[40:41]
	s_nop 0
	v_pk_add_f32 v[0:1], v[0:1], v[42:43]
	s_waitcnt vmcnt(4)
	v_pk_add_f32 v[0:1], v[0:1], v[44:45]
	s_nop 0
	v_pk_add_f32 v[0:1], v[0:1], v[46:47]
	s_waitcnt vmcnt(3)
	v_pk_add_f32 v[0:1], v[0:1], v[48:49]
	s_nop 0
	v_pk_add_f32 v[0:1], v[0:1], v[50:51]
	s_waitcnt vmcnt(2)
	v_pk_add_f32 v[0:1], v[0:1], v[52:53]
	s_nop 0
	v_pk_add_f32 v[0:1], v[0:1], v[54:55]
	s_waitcnt vmcnt(1)
	v_pk_add_f32 v[0:1], v[0:1], v[56:57]
	s_nop 0
	v_pk_add_f32 v[0:1], v[0:1], v[58:59]
	s_waitcnt vmcnt(0)
	v_pk_add_f32 v[0:1], v[0:1], v[60:61]
	s_nop 0
	v_pk_add_f32 v[0:1], v[0:1], v[62:63]
	s_nop 0
	v_pk_mul_f32 v[0:1], v[0:1], s[14:15] op_sel_hi:[1,0]
	s_nop 0
	v_fma_f32 v1, -v0, v0, v1
	v_max_f32_e32 v1, 0, v1
	v_add_f32_e32 v1, 0x358637bd, v1
	v_mul_f32_e32 v2, 0x4b800000, v1
	v_cmp_gt_f32_e32 vcc, s40, v1
	s_nop 1
	v_cndmask_b32_e32 v1, v1, v2, vcc
	v_rsq_f32_e32 v1, v1
	s_nop 0
	v_mul_f32_e32 v2, 0x45800000, v1
	v_cndmask_b32_e32 v1, v1, v2, vcc
	ds_write2st64_b32 v172, v0, v1 offset1:2
.LBB0_192:
	s_or_b64 exec, exec, s[18:19]
	s_lshl_b32 s18, s42, 4
	s_and_b32 s18, s18, 0x380
	v_add_u32_e32 v0, s18, v148
	v_ashrrev_i32_e32 v1, 31, v0
	v_lshlrev_b64 v[0:1], 9, v[0:1]
	v_mov_b32_e32 v10, 0
	s_lshr_b32 s43, s42, 6
	s_lshr_b32 s17, s42, 3
	v_lshl_add_u64 v[8:9], v[164:165], 0, v[0:1]
	s_mov_b64 s[18:19], 0
	v_mov_b32_e32 v7, v191
	v_mov_b32_e32 v16, v173
	v_mov_b32_e32 v17, v174
	v_mov_b32_e32 v11, v10
	s_waitcnt lgkmcnt(0)
	s_barrier
	s_waitcnt vmcnt(0)
	v_cmp_le_i32_e32 vcc, v16, v148
	v_mov_b32_e32 v0, v97
	v_mov_b32_e32 v1, v98
	v_mov_b32_e32 v2, v99
	v_mov_b32_e32 v3, v100
	v_mov_b32_e32 v4, v101
	v_mov_b32_e32 v5, v102
	v_mov_b32_e32 v6, v103
	v_cndmask_b32_e32 v12, 0, v96, vcc
	ds_read2st64_b64 v[18:21], v7 offset1:1
	v_cmp_lt_i32_e32 vcc, v16, v148
	s_add_u32 s18, s18, 32
	s_addc_u32 s19, s19, 0
	s_waitcnt vmcnt(0)
	v_cndmask_b32_e32 v13, 0, v0, vcc
	s_waitcnt lgkmcnt(0)
	v_pk_mul_f32 v[14:15], v[12:13], v[20:21]
	s_cmpk_eq_i32 s18, 0x80
	v_cvt_pk_bf16_f32 v0, v14, v15
	v_and_b32_e32 v32, 0xffff0000, v0
	v_lshlrev_b32_e32 v33, 16, v0
	v_or_b32_e32 v0, 3, v16
	v_or_b32_e32 v14, 2, v16
	v_cmp_le_i32_e32 vcc, v0, v149
	v_mul_f32_e32 v15, v18, v33
	v_lshl_add_u32 v18, v14, 2, s3
	v_cndmask_b32_e32 v21, 0, v2, vcc
	v_cmp_le_i32_e32 vcc, v14, v148
	v_lshl_add_u32 v22, v0, 2, s3
	v_or_b32_e32 v2, 4, v16
	v_cndmask_b32_e32 v20, 0, v1, vcc
	ds_read_b64 v[0:1], v18 offset:512
	v_lshl_add_u32 v14, v2, 2, s3
	ds_read_b32 v18, v18
	ds_read_b32 v22, v22
	ds_read_b32 v28, v14
	v_mul_f32_e32 v19, v19, v32
	v_add_u32_e32 v7, 32, v7
	s_waitcnt lgkmcnt(3)
	v_pk_mul_f32 v[0:1], v[20:21], v[0:1]
	s_nop 0
	v_cvt_pk_bf16_f32 v0, v0, v1
	v_and_b32_e32 v34, 0xffff0000, v0
	v_lshlrev_b32_e32 v35, 16, v0
	v_or_b32_e32 v0, 5, v16
	v_cmp_le_i32_e32 vcc, v0, v149
	s_waitcnt lgkmcnt(2)
	v_mul_f32_e32 v1, v18, v35
	v_lshl_add_u32 v18, v0, 2, s3
	v_cndmask_b32_e32 v25, 0, v4, vcc
	v_cmp_le_i32_e32 vcc, v2, v148
	v_or_b32_e32 v0, 6, v16
	v_lshl_add_u32 v4, v0, 2, s3
	v_cndmask_b32_e32 v24, 0, v3, vcc
	ds_read_b64 v[2:3], v14 offset:512
	ds_read_b32 v14, v18
	ds_read_b32 v18, v4
	ds_read_b64 v[26:27], v4 offset:512
	s_waitcnt lgkmcnt(5)
	v_mul_f32_e32 v23, v22, v34
	v_mov_b32_e32 v22, v21
	s_waitcnt lgkmcnt(3)
	v_pk_mul_f32 v[2:3], v[24:25], v[2:3]
	s_nop 0
	v_cvt_pk_bf16_f32 v2, v2, v3
	v_and_b32_e32 v36, 0xffff0000, v2
	v_lshlrev_b32_e32 v37, 16, v2
	v_or_b32_e32 v2, 7, v16
	v_cmp_le_i32_e32 vcc, v2, v149
	s_waitcnt lgkmcnt(2)
	v_mul_f32_e32 v29, v14, v36
	v_mov_b32_e32 v14, v12
	v_cndmask_b32_e32 v31, 0, v6, vcc
	v_cmp_le_i32_e32 vcc, v0, v148
	v_pk_add_f32 v[10:11], v[10:11], v[14:15]
	v_mul_f32_e32 v3, v28, v37
	v_cndmask_b32_e32 v30, 0, v5, vcc
	s_waitcnt lgkmcnt(0)
	v_pk_mul_f32 v[4:5], v[30:31], v[26:27]
	v_lshl_add_u32 v28, v2, 2, s3
	v_cvt_pk_bf16_f32 v0, v4, v5
	v_lshlrev_b32_e32 v26, 16, v0
	v_mul_f32_e32 v5, v18, v26
	v_mov_b32_e32 v18, v13
	v_and_b32_e32 v6, 0xffff0000, v0
	v_pk_add_f32 v[10:11], v[18:19], v[10:11]
	v_mov_b32_e32 v0, v20
	v_pk_add_f32 v[0:1], v[0:1], v[10:11]
	v_mov_b32_e32 v2, v24
	v_pk_add_f32 v[0:1], v[22:23], v[0:1]
	v_mov_b32_e32 v4, v30
	v_pk_add_f32 v[0:1], v[2:3], v[0:1]
	ds_read_b32 v2, v28
	v_mov_b32_e32 v28, v25
	v_pk_add_f32 v[0:1], v[28:29], v[0:1]
	v_add_u32_e32 v16, 8, v16
	v_pk_add_f32 v[0:1], v[4:5], v[0:1]
	s_waitcnt lgkmcnt(0)
	v_mul_f32_e32 v3, v2, v6
	v_mov_b32_e32 v2, v31
	v_pk_add_f32 v[10:11], v[2:3], v[0:1]
	v_cvt_pk_bf16_f32 v0, v33, v32
	v_cvt_pk_bf16_f32 v1, v35, v34
	v_cvt_pk_bf16_f32 v2, v37, v36
	v_cvt_pk_bf16_f32 v3, v26, v6
	ds_write_b128 v17, v[0:3]
	v_add_u32_e32 v17, 16, v17
	v_cmp_le_i32_e32 vcc, v16, v148
	v_mov_b32_e32 v0, v105
	v_mov_b32_e32 v1, v106
	v_mov_b32_e32 v2, v107
	v_mov_b32_e32 v3, v108
	v_mov_b32_e32 v4, v109
	v_mov_b32_e32 v5, v110
	v_mov_b32_e32 v6, v111
	v_cndmask_b32_e32 v12, 0, v104, vcc
	ds_read2st64_b64 v[18:21], v7 offset1:1
	v_cmp_lt_i32_e32 vcc, v16, v148
	s_add_u32 s18, s18, 32
	s_addc_u32 s19, s19, 0
	s_waitcnt vmcnt(0)
	v_cndmask_b32_e32 v13, 0, v0, vcc
	s_waitcnt lgkmcnt(0)
	v_pk_mul_f32 v[14:15], v[12:13], v[20:21]
	s_cmpk_eq_i32 s18, 0x80
	v_cvt_pk_bf16_f32 v0, v14, v15
	v_and_b32_e32 v32, 0xffff0000, v0
	v_lshlrev_b32_e32 v33, 16, v0
	v_or_b32_e32 v0, 3, v16
	v_or_b32_e32 v14, 2, v16
	v_cmp_le_i32_e32 vcc, v0, v149
	v_mul_f32_e32 v15, v18, v33
	v_lshl_add_u32 v18, v14, 2, s3
	v_cndmask_b32_e32 v21, 0, v2, vcc
	v_cmp_le_i32_e32 vcc, v14, v148
	v_lshl_add_u32 v22, v0, 2, s3
	v_or_b32_e32 v2, 4, v16
	v_cndmask_b32_e32 v20, 0, v1, vcc
	ds_read_b64 v[0:1], v18 offset:512
	v_lshl_add_u32 v14, v2, 2, s3
	ds_read_b32 v18, v18
	ds_read_b32 v22, v22
	ds_read_b32 v28, v14
	v_mul_f32_e32 v19, v19, v32
	v_add_u32_e32 v7, 32, v7
	s_waitcnt lgkmcnt(3)
	v_pk_mul_f32 v[0:1], v[20:21], v[0:1]
	s_nop 0
	v_cvt_pk_bf16_f32 v0, v0, v1
	v_and_b32_e32 v34, 0xffff0000, v0
	v_lshlrev_b32_e32 v35, 16, v0
	v_or_b32_e32 v0, 5, v16
	v_cmp_le_i32_e32 vcc, v0, v149
	s_waitcnt lgkmcnt(2)
	v_mul_f32_e32 v1, v18, v35
	v_lshl_add_u32 v18, v0, 2, s3
	v_cndmask_b32_e32 v25, 0, v4, vcc
	v_cmp_le_i32_e32 vcc, v2, v148
	v_or_b32_e32 v0, 6, v16
	v_lshl_add_u32 v4, v0, 2, s3
	v_cndmask_b32_e32 v24, 0, v3, vcc
	ds_read_b64 v[2:3], v14 offset:512
	ds_read_b32 v14, v18
	ds_read_b32 v18, v4
	ds_read_b64 v[26:27], v4 offset:512
	s_waitcnt lgkmcnt(5)
	v_mul_f32_e32 v23, v22, v34
	v_mov_b32_e32 v22, v21
	s_waitcnt lgkmcnt(3)
	v_pk_mul_f32 v[2:3], v[24:25], v[2:3]
	s_nop 0
	v_cvt_pk_bf16_f32 v2, v2, v3
	v_and_b32_e32 v36, 0xffff0000, v2
	v_lshlrev_b32_e32 v37, 16, v2
	v_or_b32_e32 v2, 7, v16
	v_cmp_le_i32_e32 vcc, v2, v149
	s_waitcnt lgkmcnt(2)
	v_mul_f32_e32 v29, v14, v36
	v_mov_b32_e32 v14, v12
	v_cndmask_b32_e32 v31, 0, v6, vcc
	v_cmp_le_i32_e32 vcc, v0, v148
	v_pk_add_f32 v[10:11], v[10:11], v[14:15]
	v_mul_f32_e32 v3, v28, v37
	v_cndmask_b32_e32 v30, 0, v5, vcc
	s_waitcnt lgkmcnt(0)
	v_pk_mul_f32 v[4:5], v[30:31], v[26:27]
	v_lshl_add_u32 v28, v2, 2, s3
	v_cvt_pk_bf16_f32 v0, v4, v5
	v_lshlrev_b32_e32 v26, 16, v0
	v_mul_f32_e32 v5, v18, v26
	v_mov_b32_e32 v18, v13
	v_and_b32_e32 v6, 0xffff0000, v0
	v_pk_add_f32 v[10:11], v[18:19], v[10:11]
	v_mov_b32_e32 v0, v20
	v_pk_add_f32 v[0:1], v[0:1], v[10:11]
	v_mov_b32_e32 v2, v24
	v_pk_add_f32 v[0:1], v[22:23], v[0:1]
	v_mov_b32_e32 v4, v30
	v_pk_add_f32 v[0:1], v[2:3], v[0:1]
	ds_read_b32 v2, v28
	v_mov_b32_e32 v28, v25
	v_pk_add_f32 v[0:1], v[28:29], v[0:1]
	v_add_u32_e32 v16, 8, v16
	v_pk_add_f32 v[0:1], v[4:5], v[0:1]
	s_waitcnt lgkmcnt(0)
	v_mul_f32_e32 v3, v2, v6
	v_mov_b32_e32 v2, v31
	v_pk_add_f32 v[10:11], v[2:3], v[0:1]
	v_cvt_pk_bf16_f32 v0, v33, v32
	v_cvt_pk_bf16_f32 v1, v35, v34
	v_cvt_pk_bf16_f32 v2, v37, v36
	v_cvt_pk_bf16_f32 v3, v26, v6
	ds_write_b128 v17, v[0:3]
	v_add_u32_e32 v17, 16, v17
	v_cmp_le_i32_e32 vcc, v16, v148
	v_mov_b32_e32 v0, v113
	v_mov_b32_e32 v1, v114
	v_mov_b32_e32 v2, v115
	v_mov_b32_e32 v3, v116
	v_mov_b32_e32 v4, v117
	v_mov_b32_e32 v5, v118
	v_mov_b32_e32 v6, v119
	v_cndmask_b32_e32 v12, 0, v112, vcc
	ds_read2st64_b64 v[18:21], v7 offset1:1
	v_cmp_lt_i32_e32 vcc, v16, v148
	s_add_u32 s18, s18, 32
	s_addc_u32 s19, s19, 0
	s_waitcnt vmcnt(0)
	v_cndmask_b32_e32 v13, 0, v0, vcc
	s_waitcnt lgkmcnt(0)
	v_pk_mul_f32 v[14:15], v[12:13], v[20:21]
	s_cmpk_eq_i32 s18, 0x80
	v_cvt_pk_bf16_f32 v0, v14, v15
	v_and_b32_e32 v32, 0xffff0000, v0
	v_lshlrev_b32_e32 v33, 16, v0
	v_or_b32_e32 v0, 3, v16
	v_or_b32_e32 v14, 2, v16
	v_cmp_le_i32_e32 vcc, v0, v149
	v_mul_f32_e32 v15, v18, v33
	v_lshl_add_u32 v18, v14, 2, s3
	v_cndmask_b32_e32 v21, 0, v2, vcc
	v_cmp_le_i32_e32 vcc, v14, v148
	v_lshl_add_u32 v22, v0, 2, s3
	v_or_b32_e32 v2, 4, v16
	v_cndmask_b32_e32 v20, 0, v1, vcc
	ds_read_b64 v[0:1], v18 offset:512
	v_lshl_add_u32 v14, v2, 2, s3
	ds_read_b32 v18, v18
	ds_read_b32 v22, v22
	ds_read_b32 v28, v14
	v_mul_f32_e32 v19, v19, v32
	v_add_u32_e32 v7, 32, v7
	s_waitcnt lgkmcnt(3)
	v_pk_mul_f32 v[0:1], v[20:21], v[0:1]
	s_nop 0
	v_cvt_pk_bf16_f32 v0, v0, v1
	v_and_b32_e32 v34, 0xffff0000, v0
	v_lshlrev_b32_e32 v35, 16, v0
	v_or_b32_e32 v0, 5, v16
	v_cmp_le_i32_e32 vcc, v0, v149
	s_waitcnt lgkmcnt(2)
	v_mul_f32_e32 v1, v18, v35
	v_lshl_add_u32 v18, v0, 2, s3
	v_cndmask_b32_e32 v25, 0, v4, vcc
	v_cmp_le_i32_e32 vcc, v2, v148
	v_or_b32_e32 v0, 6, v16
	v_lshl_add_u32 v4, v0, 2, s3
	v_cndmask_b32_e32 v24, 0, v3, vcc
	ds_read_b64 v[2:3], v14 offset:512
	ds_read_b32 v14, v18
	ds_read_b32 v18, v4
	ds_read_b64 v[26:27], v4 offset:512
	s_waitcnt lgkmcnt(5)
	v_mul_f32_e32 v23, v22, v34
	v_mov_b32_e32 v22, v21
	s_waitcnt lgkmcnt(3)
	v_pk_mul_f32 v[2:3], v[24:25], v[2:3]
	s_nop 0
	v_cvt_pk_bf16_f32 v2, v2, v3
	v_and_b32_e32 v36, 0xffff0000, v2
	v_lshlrev_b32_e32 v37, 16, v2
	v_or_b32_e32 v2, 7, v16
	v_cmp_le_i32_e32 vcc, v2, v149
	s_waitcnt lgkmcnt(2)
	v_mul_f32_e32 v29, v14, v36
	v_mov_b32_e32 v14, v12
	v_cndmask_b32_e32 v31, 0, v6, vcc
	v_cmp_le_i32_e32 vcc, v0, v148
	v_pk_add_f32 v[10:11], v[10:11], v[14:15]
	v_mul_f32_e32 v3, v28, v37
	v_cndmask_b32_e32 v30, 0, v5, vcc
	s_waitcnt lgkmcnt(0)
	v_pk_mul_f32 v[4:5], v[30:31], v[26:27]
	v_lshl_add_u32 v28, v2, 2, s3
	v_cvt_pk_bf16_f32 v0, v4, v5
	v_lshlrev_b32_e32 v26, 16, v0
	v_mul_f32_e32 v5, v18, v26
	v_mov_b32_e32 v18, v13
	v_and_b32_e32 v6, 0xffff0000, v0
	v_pk_add_f32 v[10:11], v[18:19], v[10:11]
	v_mov_b32_e32 v0, v20
	v_pk_add_f32 v[0:1], v[0:1], v[10:11]
	v_mov_b32_e32 v2, v24
	v_pk_add_f32 v[0:1], v[22:23], v[0:1]
	v_mov_b32_e32 v4, v30
	v_pk_add_f32 v[0:1], v[2:3], v[0:1]
	ds_read_b32 v2, v28
	v_mov_b32_e32 v28, v25
	v_pk_add_f32 v[0:1], v[28:29], v[0:1]
	v_add_u32_e32 v16, 8, v16
	v_pk_add_f32 v[0:1], v[4:5], v[0:1]
	s_waitcnt lgkmcnt(0)
	v_mul_f32_e32 v3, v2, v6
	v_mov_b32_e32 v2, v31
	v_pk_add_f32 v[10:11], v[2:3], v[0:1]
	v_cvt_pk_bf16_f32 v0, v33, v32
	v_cvt_pk_bf16_f32 v1, v35, v34
	v_cvt_pk_bf16_f32 v2, v37, v36
	v_cvt_pk_bf16_f32 v3, v26, v6
	ds_write_b128 v17, v[0:3]
	v_add_u32_e32 v17, 16, v17
	v_cmp_le_i32_e32 vcc, v16, v148
	v_mov_b32_e32 v0, v121
	v_mov_b32_e32 v1, v122
	v_mov_b32_e32 v2, v123
	v_mov_b32_e32 v3, v124
	v_mov_b32_e32 v4, v125
	v_mov_b32_e32 v5, v126
	v_mov_b32_e32 v6, v127
	v_cndmask_b32_e32 v12, 0, v120, vcc
	ds_read2st64_b64 v[18:21], v7 offset1:1
	v_cmp_lt_i32_e32 vcc, v16, v148
	s_add_u32 s18, s18, 32
	s_addc_u32 s19, s19, 0
	s_waitcnt vmcnt(0)
	v_cndmask_b32_e32 v13, 0, v0, vcc
	s_waitcnt lgkmcnt(0)
	v_pk_mul_f32 v[14:15], v[12:13], v[20:21]
	s_cmpk_eq_i32 s18, 0x80
	v_cvt_pk_bf16_f32 v0, v14, v15
	v_and_b32_e32 v32, 0xffff0000, v0
	v_lshlrev_b32_e32 v33, 16, v0
	v_or_b32_e32 v0, 3, v16
	v_or_b32_e32 v14, 2, v16
	v_cmp_le_i32_e32 vcc, v0, v149
	v_mul_f32_e32 v15, v18, v33
	v_lshl_add_u32 v18, v14, 2, s3
	v_cndmask_b32_e32 v21, 0, v2, vcc
	v_cmp_le_i32_e32 vcc, v14, v148
	v_lshl_add_u32 v22, v0, 2, s3
	v_or_b32_e32 v2, 4, v16
	v_cndmask_b32_e32 v20, 0, v1, vcc
	ds_read_b64 v[0:1], v18 offset:512
	v_lshl_add_u32 v14, v2, 2, s3
	ds_read_b32 v18, v18
	ds_read_b32 v22, v22
	ds_read_b32 v28, v14
	v_mul_f32_e32 v19, v19, v32
	v_add_u32_e32 v7, 32, v7
	s_waitcnt lgkmcnt(3)
	v_pk_mul_f32 v[0:1], v[20:21], v[0:1]
	s_nop 0
	v_cvt_pk_bf16_f32 v0, v0, v1
	v_and_b32_e32 v34, 0xffff0000, v0
	v_lshlrev_b32_e32 v35, 16, v0
	v_or_b32_e32 v0, 5, v16
	v_cmp_le_i32_e32 vcc, v0, v149
	s_waitcnt lgkmcnt(2)
	v_mul_f32_e32 v1, v18, v35
	v_lshl_add_u32 v18, v0, 2, s3
	v_cndmask_b32_e32 v25, 0, v4, vcc
	v_cmp_le_i32_e32 vcc, v2, v148
	v_or_b32_e32 v0, 6, v16
	v_lshl_add_u32 v4, v0, 2, s3
	v_cndmask_b32_e32 v24, 0, v3, vcc
	ds_read_b64 v[2:3], v14 offset:512
	ds_read_b32 v14, v18
	ds_read_b32 v18, v4
	ds_read_b64 v[26:27], v4 offset:512
	s_waitcnt lgkmcnt(5)
	v_mul_f32_e32 v23, v22, v34
	v_mov_b32_e32 v22, v21
	s_waitcnt lgkmcnt(3)
	v_pk_mul_f32 v[2:3], v[24:25], v[2:3]
	s_nop 0
	v_cvt_pk_bf16_f32 v2, v2, v3
	v_and_b32_e32 v36, 0xffff0000, v2
	v_lshlrev_b32_e32 v37, 16, v2
	v_or_b32_e32 v2, 7, v16
	v_cmp_le_i32_e32 vcc, v2, v149
	s_waitcnt lgkmcnt(2)
	v_mul_f32_e32 v29, v14, v36
	v_mov_b32_e32 v14, v12
	v_cndmask_b32_e32 v31, 0, v6, vcc
	v_cmp_le_i32_e32 vcc, v0, v148
	v_pk_add_f32 v[10:11], v[10:11], v[14:15]
	v_mul_f32_e32 v3, v28, v37
	v_cndmask_b32_e32 v30, 0, v5, vcc
	s_waitcnt lgkmcnt(0)
	v_pk_mul_f32 v[4:5], v[30:31], v[26:27]
	v_lshl_add_u32 v28, v2, 2, s3
	v_cvt_pk_bf16_f32 v0, v4, v5
	v_lshlrev_b32_e32 v26, 16, v0
	v_mul_f32_e32 v5, v18, v26
	v_mov_b32_e32 v18, v13
	v_and_b32_e32 v6, 0xffff0000, v0
	v_pk_add_f32 v[10:11], v[18:19], v[10:11]
	v_mov_b32_e32 v0, v20
	v_pk_add_f32 v[0:1], v[0:1], v[10:11]
	v_mov_b32_e32 v2, v24
	v_pk_add_f32 v[0:1], v[22:23], v[0:1]
	v_mov_b32_e32 v4, v30
	v_pk_add_f32 v[0:1], v[2:3], v[0:1]
	ds_read_b32 v2, v28
	v_mov_b32_e32 v28, v25
	v_pk_add_f32 v[0:1], v[28:29], v[0:1]
	v_add_u32_e32 v16, 8, v16
	v_pk_add_f32 v[0:1], v[4:5], v[0:1]
	s_waitcnt lgkmcnt(0)
	v_mul_f32_e32 v3, v2, v6
	v_mov_b32_e32 v2, v31
	v_pk_add_f32 v[10:11], v[2:3], v[0:1]
	v_cvt_pk_bf16_f32 v0, v33, v32
	v_cvt_pk_bf16_f32 v1, v35, v34
	v_cvt_pk_bf16_f32 v2, v37, v36
	v_cvt_pk_bf16_f32 v3, v26, v6
	ds_write_b128 v17, v[0:3]
	v_add_u32_e32 v17, 16, v17

.LBB0_199:
	s_waitcnt lgkmcnt(0)
	v_ashrrev_i32_e32 v250, 4, v153
	v_mul_lo_u32 v250, v250, s15
	v_add_u32_e32 v250, v250, v152
	s_lshl_b32 s48, s15, 5
	ds_write_b128 v250, v[64:67] offset:18432
	v_add_u32_e32 v250, s48, v250
	ds_write_b128 v250, v[68:71] offset:18432
	v_add_u32_e32 v250, s48, v250
	ds_write_b128 v250, v[72:75] offset:18432
	v_add_u32_e32 v250, s48, v250
	ds_write_b128 v250, v[76:79] offset:18432
	v_add_u32_e32 v250, s48, v250
	ds_write_b128 v250, v[80:83] offset:18432
	v_add_u32_e32 v250, s48, v250
	ds_write_b128 v250, v[84:87] offset:18432
	v_add_u32_e32 v250, s48, v250
	ds_write_b128 v250, v[88:91] offset:18432
	v_add_u32_e32 v250, s48, v250
	ds_write_b128 v250, v[92:95] offset:18432
	s_movk_i32 s22, 0x1000
	s_waitcnt lgkmcnt(0)
	s_barrier
	ds_read_b128 v[0:3], v154
	ds_read_b128 v[8:11], v155 offset:18432
	ds_read_b128 v[136:139], v154 offset:32
	ds_read_b128 v[12:15], v155 offset:18464
	ds_read_b128 v[4:7], v154 offset:4608
	ds_read_b128 v[132:135], v154 offset:4640
	s_waitcnt lgkmcnt(4)
	v_mfma_f32_32x32x16_bf16 v[48:63], v[0:3], v[8:11], 0
	s_and_b32 s16, s41, 7
	s_lshl_b32 s12, s12, 1
	s_lshl_b32 s16, s16, 1
	s_and_b32 s12, s12, 0x1fffff0
	s_and_b32 s17, s43, 1
	s_or_b32 s12, s12, s16
	s_or_b32 s12, s12, s17
	s_waitcnt lgkmcnt(1)
	v_mfma_f32_32x32x16_bf16 v[32:47], v[4:7], v[8:11], 0
	s_mov_b64 s[16:17], 0
	v_mfma_f32_32x32x16_bf16 v[48:63], v[136:139], v[12:15], v[48:63]
	s_waitcnt lgkmcnt(0)
	v_mfma_f32_32x32x16_bf16 v[32:47], v[132:135], v[12:15], v[32:47]
	ds_read_b128 v[128:131], v154 offset:64
	ds_read_b128 v[8:11], v155 offset:18496
	ds_read_b128 v[116:119], v154 offset:96
	ds_read_b128 v[12:15], v155 offset:18528
	ds_read_b128 v[124:127], v154 offset:4672
	ds_read_b128 v[112:115], v154 offset:4704
	s_waitcnt lgkmcnt(4)
	v_mfma_f32_32x32x16_bf16 v[48:63], v[128:131], v[8:11], v[48:63]
	s_waitcnt lgkmcnt(1)
	v_mfma_f32_32x32x16_bf16 v[32:47], v[124:127], v[8:11], v[32:47]
	v_mfma_f32_32x32x16_bf16 v[48:63], v[116:119], v[12:15], v[48:63]
	s_waitcnt lgkmcnt(0)
	v_mfma_f32_32x32x16_bf16 v[32:47], v[112:115], v[12:15], v[32:47]
	ds_read_b128 v[108:111], v154 offset:55296
	ds_read_b128 v[8:11], v180
	ds_read_b128 v[12:15], v180 offset:32
	ds_read_b128 v[92:95], v154 offset:55328
	ds_read_b128 v[100:103], v154 offset:59904
	ds_read_b128 v[88:91], v154 offset:59936
	ds_read_b128 v[84:87], v154 offset:55360
	s_waitcnt lgkmcnt(5)
	v_mfma_f32_32x32x16_bf16 v[48:63], v[108:111], v[8:11], v[48:63]
	s_waitcnt lgkmcnt(2)
	v_mfma_f32_32x32x16_bf16 v[32:47], v[100:103], v[8:11], v[32:47]
	v_mfma_f32_32x32x16_bf16 v[48:63], v[92:95], v[12:15], v[48:63]
	s_waitcnt lgkmcnt(1)
	v_mfma_f32_32x32x16_bf16 v[32:47], v[88:91], v[12:15], v[32:47]
	ds_read_b128 v[12:15], v180 offset:64
	ds_read_b128 v[72:75], v154 offset:59968
	ds_read_b128 v[80:83], v154 offset:55392
	ds_read_b128 v[16:19], v180 offset:96
	ds_read_b128 v[8:11], v155 offset:23040
	ds_read_b128 v[144:147], v155 offset:23072
	ds_read_b128 v[140:143], v155 offset:23104
	ds_read_b128 v[120:123], v155 offset:23136
	ds_read_b128 v[104:107], v180 offset:4608
	ds_read_b128 v[96:99], v180 offset:4640
	ds_read_b128 v[64:67], v154 offset:60000
	ds_read_b128 v[76:79], v180 offset:4672
	ds_read_b128 v[68:71], v180 offset:4704
	s_waitcnt lgkmcnt(0)
	s_barrier
	v_mfma_f32_32x32x16_bf16 v[48:63], v[84:87], v[12:15], v[48:63]
	v_mfma_f32_32x32x16_bf16 v[32:47], v[72:75], v[12:15], v[32:47]
	v_lshl_add_u32 v12, s12, 7, v178
	v_ashrrev_i32_e32 v13, 31, v12
	v_lshlrev_b64 v[12:13], 12, v[12:13]
	v_lshl_or_b32 v12, s18, 9, v12
	v_lshl_add_u64 v[168:169], v[166:167], 0, v[12:13]
	v_mov_b32_e32 v12, v192
	v_mfma_f32_32x32x16_bf16 v[48:63], v[80:83], v[16:19], v[48:63]
	v_mfma_f32_32x32x16_bf16 v[32:47], v[64:67], v[16:19], v[32:47]
.LBB0_201:
	s_waitcnt vmcnt(0)
	ds_write_b128 v192, v[216:219]
	ds_write_b128 v192, v[220:223] offset:1152
	ds_write_b128 v192, v[224:227] offset:2304
	ds_write_b128 v192, v[228:231] offset:3456
	ds_write_b128 v192, v[232:235] offset:4608
	ds_write_b128 v192, v[236:239] offset:5760
	ds_write_b128 v192, v[240:243] offset:6912
	ds_write_b128 v192, v[244:247] offset:8064
	v_mfma_f32_32x32x16_bf16 v[16:31], v[0:3], v[8:11], 0
	v_add_u32_e32 v170, s19, v179
	v_ashrrev_i32_e32 v171, 31, v170
	v_lshlrev_b64 v[194:195], 2, v[170:171]
	v_lshl_add_u64 v[170:171], s[46:47], 0, v[194:195]
	s_lshl_b32 s12, s18, 7
	s_waitcnt lgkmcnt(0)
	s_mov_b64 s[16:17], 0
	v_mfma_f32_32x32x16_bf16 v[0:15], v[4:7], v[8:11], 0
	v_mfma_f32_32x32x16_bf16 v[16:31], v[136:139], v[144:147], v[16:31]
	global_load_dword v138, v[170:171], off
	v_lshl_add_u64 v[136:137], s[44:45], 0, v[194:195]
	v_add_u32_e32 v194, s12, v156
	global_load_dword v139, v[136:137], off
	v_ashrrev_i32_e32 v195, 31, v194
	v_mfma_f32_32x32x16_bf16 v[0:15], v[132:135], v[144:147], v[0:15]
	v_lshl_add_u64 v[134:135], v[194:195], 2, s[50:51]
	v_lshl_add_u64 v[132:133], s[12:13], 0, v[156:157]
	v_lshl_add_u64 v[132:133], v[132:133], 2, s[50:51]
	global_load_dword v213, v[134:135], off
	global_load_dwordx3 v[210:212], v[132:133], off offset:4
	v_mfma_f32_32x32x16_bf16 v[16:31], v[128:131], v[140:143], v[16:31]
	global_load_dwordx4 v[128:131], v[132:133], off offset:32
	ds_read_b128 v[144:147], v182 offset:1536
	ds_read_b128 v[194:197], v182 offset:1024
	s_waitcnt lgkmcnt(1)
	v_sub_f32_e32 v48, v48, v144
	v_sub_f32_e32 v49, v49, v145
	v_mfma_f32_32x32x16_bf16 v[0:15], v[124:127], v[140:143], v[0:15]
	ds_read_u16 v214, v183
	ds_read_b128 v[124:127], v184 offset:1024
	ds_read_b128 v[140:143], v184 offset:1536
	ds_read_b128 v[198:201], v185 offset:1024
	global_load_dwordx4 v[202:205], v[132:133], off offset:64
	global_load_dwordx4 v[206:209], v[132:133], off offset:96
	s_waitcnt lgkmcnt(3)
	v_lshlrev_b32_e32 v144, 16, v214
	v_sub_f32_e32 v50, v50, v146
	v_sub_f32_e32 v51, v51, v147
	s_waitcnt lgkmcnt(1)
	v_sub_f32_e32 v52, v52, v140
	v_sub_f32_e32 v53, v53, v141
	v_mfma_f32_32x32x16_bf16 v[0:15], v[112:115], v[120:123], v[0:15]
	v_sub_f32_e32 v54, v54, v142
	v_sub_f32_e32 v55, v55, v143
	s_waitcnt vmcnt(6)
	v_mul_f32_e32 v112, v138, v194
	v_mfma_f32_32x32x16_bf16 v[16:31], v[116:119], v[120:123], v[16:31]
	v_mul_f32_e32 v113, v138, v195
	s_waitcnt vmcnt(5)
	v_fmac_f32_e32 v112, v139, v48
	v_mul_f32_e32 v114, v138, v196
	v_mul_f32_e32 v115, v138, v197
	v_mul_f32_e32 v116, v138, v124
	v_mul_f32_e32 v117, v138, v125
	v_mul_f32_e32 v118, v138, v126
	v_fmac_f32_e32 v113, v139, v49
	s_waitcnt vmcnt(4)
	v_add_f32_e32 v48, v213, v112
	v_mul_f32_e32 v48, v48, v144
	v_cvt_pk_bf16_f32 v48, v48, s0
	v_fmac_f32_e32 v114, v139, v50
	v_fmac_f32_e32 v115, v139, v51
	v_fmac_f32_e32 v116, v139, v52
	v_fmac_f32_e32 v117, v139, v53
	v_fmac_f32_e32 v118, v139, v54
	ds_write_b16 v183, v48
	s_waitcnt vmcnt(3)
	v_add_f32_e32 v49, v210, v113
	v_add_f32_e32 v50, v211, v114
	v_add_f32_e32 v51, v212, v115
	s_waitcnt vmcnt(2)
	v_add_f32_e32 v52, v128, v116
	v_add_f32_e32 v53, v129, v117
	v_add_f32_e32 v54, v130, v118
	ds_read_u16 v48, v193
	ds_read_u16 v112, v193 offset:144
	ds_read_u16 v113, v193 offset:288
	ds_read_u16 v114, v193 offset:1008
	ds_read_u16 v115, v193 offset:1152
	ds_read_u16 v116, v193 offset:1296
	ds_read_u16 v117, v193 offset:1440
	ds_read_u16 v118, v193 offset:2160
	s_waitcnt lgkmcnt(7)
	v_lshlrev_b32_e32 v48, 16, v48
	s_waitcnt lgkmcnt(6)
	v_lshlrev_b32_e32 v112, 16, v112
	s_waitcnt lgkmcnt(5)
	v_lshlrev_b32_e32 v113, 16, v113
	s_waitcnt lgkmcnt(4)
	v_lshlrev_b32_e32 v114, 16, v114
	s_waitcnt lgkmcnt(3)
	v_lshlrev_b32_e32 v115, 16, v115
	s_waitcnt lgkmcnt(2)
	v_lshlrev_b32_e32 v116, 16, v116
	v_mul_f32_e32 v48, v49, v48
	v_mul_f32_e32 v49, v50, v112
	v_mul_f32_e32 v50, v51, v113
	v_mul_f32_e32 v51, v52, v114
	v_mul_f32_e32 v52, v53, v115
	v_mul_f32_e32 v53, v54, v116
	v_cvt_pk_bf16_f32 v48, v48, s0
	v_cvt_pk_bf16_f32 v49, v49, s0
	v_cvt_pk_bf16_f32 v50, v50, s0
	v_cvt_pk_bf16_f32 v51, v51, s0
	v_cvt_pk_bf16_f32 v52, v52, s0
	v_cvt_pk_bf16_f32 v53, v53, s0
	ds_write_b16 v193, v48
	ds_write_b16 v193, v49 offset:144
	ds_write_b16 v193, v50 offset:288
	ds_write_b16 v193, v51 offset:1008
	ds_write_b16 v193, v52 offset:1152
	ds_write_b16 v193, v53 offset:1296
	ds_read_b128 v[48:51], v185 offset:1536
	v_mul_f32_e32 v119, v138, v127
	v_fmac_f32_e32 v119, v139, v55
	v_add_f32_e32 v52, v131, v119
	s_waitcnt lgkmcnt(8)
	v_lshlrev_b32_e32 v53, 16, v117
	s_waitcnt lgkmcnt(0)
	v_sub_f32_e32 v48, v56, v48
	v_mul_f32_e32 v56, v138, v198
	v_fmac_f32_e32 v56, v139, v48
	s_waitcnt vmcnt(1)
	v_add_f32_e32 v48, v202, v56
	v_lshlrev_b32_e32 v56, 16, v118
	v_mul_f32_e32 v48, v48, v56
	v_mul_f32_e32 v52, v52, v53
	v_cvt_pk_bf16_f32 v48, v48, s0
	v_cvt_pk_bf16_f32 v52, v52, s0
	ds_write_b16 v193, v48 offset:2160
	v_sub_f32_e32 v48, v57, v49
	v_mul_f32_e32 v49, v138, v199
	ds_write_b16 v193, v52 offset:1440
	v_fmac_f32_e32 v49, v139, v48
	ds_read_b128 v[52:55], v186 offset:1024
	v_add_f32_e32 v48, v203, v49
	ds_read_u16 v49, v193 offset:2304
	ds_read_u16 v56, v193 offset:2448
	ds_read_u16 v57, v193 offset:2592
	ds_read_u16 v112, v193 offset:3312
	ds_read_u16 v113, v193 offset:3456
	ds_read_u16 v114, v193 offset:3600
	ds_read_u16 v115, v193 offset:3744
	s_waitcnt lgkmcnt(6)
	v_lshlrev_b32_e32 v49, 16, v49
	v_mul_f32_e32 v48, v48, v49
	v_cvt_pk_bf16_f32 v48, v48, s0
	ds_write_b16 v193, v48 offset:2304
	v_sub_f32_e32 v48, v58, v50
	v_mul_f32_e32 v49, v138, v200
	v_fmac_f32_e32 v49, v139, v48
	v_add_f32_e32 v48, v204, v49
	s_waitcnt lgkmcnt(6)
	v_lshlrev_b32_e32 v49, 16, v56
	v_mul_f32_e32 v48, v48, v49
	v_cvt_pk_bf16_f32 v48, v48, s0
	ds_write_b16 v193, v48 offset:2448
	v_sub_f32_e32 v48, v59, v51
	v_mul_f32_e32 v49, v138, v201
	v_fmac_f32_e32 v49, v139, v48
	v_add_f32_e32 v56, v205, v49
	ds_read_b128 v[48:51], v186 offset:1536
	v_mul_f32_e32 v52, v138, v52
	s_waitcnt lgkmcnt(7)
	v_lshlrev_b32_e32 v57, 16, v57
	v_mul_f32_e32 v56, v56, v57
	v_cvt_pk_bf16_f32 v56, v56, s0
	s_waitcnt lgkmcnt(0)
	v_sub_f32_e32 v48, v60, v48
	v_fmac_f32_e32 v52, v139, v48
	s_waitcnt vmcnt(0)
	v_add_f32_e32 v48, v206, v52
	v_lshlrev_b32_e32 v52, 16, v112
	v_mul_f32_e32 v48, v48, v52
	v_cvt_pk_bf16_f32 v48, v48, s0
	ds_write_b16 v193, v48 offset:3312
	v_sub_f32_e32 v48, v61, v49
	v_mul_f32_e32 v49, v138, v53
	v_fmac_f32_e32 v49, v139, v48
	v_add_f32_e32 v48, v207, v49
	v_lshlrev_b32_e32 v49, 16, v113
	v_mul_f32_e32 v48, v48, v49
	v_cvt_pk_bf16_f32 v48, v48, s0
	ds_write_b16 v193, v48 offset:3456
	v_sub_f32_e32 v48, v62, v50
	v_mul_f32_e32 v49, v138, v54
	v_fmac_f32_e32 v49, v139, v48
	v_add_f32_e32 v48, v208, v49
	v_lshlrev_b32_e32 v49, 16, v114
	v_mul_f32_e32 v48, v48, v49
	v_cvt_pk_bf16_f32 v48, v48, s0
	ds_write_b16 v193, v48 offset:3600
	v_sub_f32_e32 v48, v63, v51
	v_mul_f32_e32 v49, v138, v55
	v_fmac_f32_e32 v49, v139, v48
	v_add_f32_e32 v48, v209, v49
	v_lshlrev_b32_e32 v49, 16, v115
	v_mul_f32_e32 v48, v48, v49
	v_cvt_pk_bf16_f32 v48, v48, s0
	ds_write_b16 v193, v56 offset:2592
	ds_write_b16 v193, v48 offset:3744
	global_load_dwordx4 v[52:55], v[132:133], off offset:128
	v_lshl_add_u64 v[48:49], s[12:13], 0, v[158:159]
	v_lshl_add_u64 v[48:49], v[48:49], 2, s[50:51]
	global_load_dwordx4 v[56:59], v[48:49], off offset:128
	v_mfma_f32_32x32x16_bf16 v[16:31], v[108:111], v[104:107], v[16:31]
	ds_read_b128 v[60:63], v187 offset:1536
	ds_read_b128 v[108:111], v187 offset:1024
	v_lshl_add_u64 v[50:51], s[12:13], 0, v[160:161]
	v_lshl_add_u64 v[50:51], v[50:51], 2, s[50:51]
	s_waitcnt lgkmcnt(1)
	v_sub_f32_e32 v32, v32, v60
	s_waitcnt lgkmcnt(0)
	v_mul_f32_e32 v60, v138, v108
	v_fmac_f32_e32 v60, v139, v32
	v_mfma_f32_32x32x16_bf16 v[0:15], v[100:103], v[104:107], v[0:15]
	global_load_dwordx4 v[100:103], v[50:51], off offset:128
	s_waitcnt vmcnt(2)
	v_add_f32_e32 v32, v52, v60
	ds_read_u16 v52, v183 offset:4608
	ds_read_u16 v60, v183 offset:4752
	ds_read_u16 v104, v183 offset:4896
	ds_read_u16 v105, v183 offset:5040
	ds_read_u16 v108, v183 offset:5760
	ds_read_u16 v112, v183 offset:5904
	ds_read_u16 v113, v183 offset:6048
	ds_read_u16 v114, v183 offset:6192
	s_waitcnt lgkmcnt(7)
	v_lshlrev_b32_e32 v52, 16, v52
	v_mul_f32_e32 v32, v32, v52
	v_cvt_pk_bf16_f32 v32, v32, s0
	ds_write_b16 v183, v32 offset:4608
	v_sub_f32_e32 v32, v33, v61
	v_mul_f32_e32 v33, v138, v109
	v_fmac_f32_e32 v33, v139, v32
	v_add_f32_e32 v32, v53, v33
	s_waitcnt lgkmcnt(7)
	v_lshlrev_b32_e32 v33, 16, v60
	v_mul_f32_e32 v32, v32, v33
	v_cvt_pk_bf16_f32 v32, v32, s0
	ds_write_b16 v183, v32 offset:4752
	v_sub_f32_e32 v32, v34, v62
	v_mul_f32_e32 v33, v138, v110
	v_fmac_f32_e32 v33, v139, v32
	v_add_f32_e32 v32, v54, v33
	s_waitcnt lgkmcnt(7)
	v_lshlrev_b32_e32 v33, 16, v104
	v_mul_f32_e32 v32, v32, v33
	v_cvt_pk_bf16_f32 v32, v32, s0
	ds_write_b16 v183, v32 offset:4896
	v_sub_f32_e32 v32, v35, v63
	v_mul_f32_e32 v33, v138, v111
	v_fmac_f32_e32 v33, v139, v32
	v_add_f32_e32 v32, v55, v33
	s_waitcnt lgkmcnt(7)
	v_lshlrev_b32_e32 v33, 16, v105
	v_mul_f32_e32 v32, v32, v33
	v_cvt_pk_bf16_f32 v32, v32, s0
	ds_write_b16 v183, v32 offset:5040
	v_lshl_add_u64 v[32:33], s[12:13], 0, v[162:163]
	v_lshl_add_u64 v[32:33], v[32:33], 2, s[50:51]
	ds_read_b128 v[52:55], v188 offset:1536
	ds_read_b128 v[60:63], v188 offset:1024
	global_load_dwordx4 v[104:107], v[32:33], off offset:128
	v_mfma_f32_32x32x16_bf16 v[16:31], v[92:95], v[96:99], v[16:31]
	s_waitcnt lgkmcnt(1)
	v_sub_f32_e32 v34, v36, v52
	s_waitcnt lgkmcnt(0)
	v_mul_f32_e32 v35, v138, v60
	v_fmac_f32_e32 v35, v139, v34
	s_waitcnt vmcnt(2)
	v_add_f32_e32 v34, v56, v35
	v_lshlrev_b32_e32 v35, 16, v108
	v_mul_f32_e32 v34, v34, v35
	v_cvt_pk_bf16_f32 v34, v34, s0
	ds_write_b16 v183, v34 offset:5760
	v_sub_f32_e32 v34, v37, v53
	v_mul_f32_e32 v35, v138, v61
	v_fmac_f32_e32 v35, v139, v34
	v_add_f32_e32 v34, v57, v35
	v_lshlrev_b32_e32 v35, 16, v112
	v_mul_f32_e32 v34, v34, v35
	v_cvt_pk_bf16_f32 v34, v34, s0
	ds_write_b16 v183, v34 offset:5904
	v_sub_f32_e32 v34, v38, v54
	v_mul_f32_e32 v35, v138, v62
	v_fmac_f32_e32 v35, v139, v34
	v_add_f32_e32 v34, v58, v35
	v_lshlrev_b32_e32 v35, 16, v113
	v_mul_f32_e32 v34, v34, v35
	v_cvt_pk_bf16_f32 v34, v34, s0
	ds_write_b16 v183, v34 offset:6048
	v_sub_f32_e32 v34, v39, v55
	v_mul_f32_e32 v35, v138, v63
	v_fmac_f32_e32 v35, v139, v34
	v_add_f32_e32 v38, v59, v35
	ds_read_b128 v[34:37], v189 offset:1536
	ds_read_b128 v[52:55], v189 offset:1024
	v_lshlrev_b32_e32 v39, 16, v114
	v_mul_f32_e32 v38, v38, v39
	v_cvt_pk_bf16_f32 v38, v38, s0
	ds_write_b16 v183, v38 offset:6192
	s_waitcnt lgkmcnt(2)
	v_sub_f32_e32 v34, v40, v34
	s_waitcnt lgkmcnt(1)
	v_mul_f32_e32 v38, v138, v52
	v_fmac_f32_e32 v38, v139, v34
	s_waitcnt vmcnt(1)
	v_add_f32_e32 v34, v100, v38
	ds_read_u16 v38, v183 offset:6912
	ds_read_u16 v39, v183 offset:7056
	ds_read_u16 v40, v183 offset:7200
	ds_read_u16 v52, v183 offset:7344
	ds_read_u16 v56, v183 offset:8064
	ds_read_u16 v57, v183 offset:8208
	ds_read_u16 v58, v183 offset:8352
	ds_read_u16 v59, v183 offset:8496
	s_waitcnt lgkmcnt(7)
	v_lshlrev_b32_e32 v38, 16, v38
	v_mul_f32_e32 v34, v34, v38
	v_cvt_pk_bf16_f32 v34, v34, s0
	ds_write_b16 v183, v34 offset:6912
	v_sub_f32_e32 v34, v41, v35
	v_mul_f32_e32 v35, v138, v53
	v_fmac_f32_e32 v35, v139, v34
	v_add_f32_e32 v34, v101, v35
	s_waitcnt lgkmcnt(7)
	v_lshlrev_b32_e32 v35, 16, v39
	v_mul_f32_e32 v34, v34, v35
	v_cvt_pk_bf16_f32 v34, v34, s0
	ds_write_b16 v183, v34 offset:7056
	v_sub_f32_e32 v34, v42, v36
	v_mul_f32_e32 v35, v138, v54
	v_fmac_f32_e32 v35, v139, v34
	v_add_f32_e32 v34, v102, v35
	s_waitcnt lgkmcnt(7)
	v_lshlrev_b32_e32 v35, 16, v40
	v_mul_f32_e32 v34, v34, v35
	v_cvt_pk_bf16_f32 v34, v34, s0
	ds_write_b16 v183, v34 offset:7200
	v_sub_f32_e32 v34, v43, v37
	v_mul_f32_e32 v35, v138, v55
	v_fmac_f32_e32 v35, v139, v34
	v_add_f32_e32 v42, v103, v35
	ds_read_b128 v[34:37], v190 offset:1536
	ds_read_b128 v[38:41], v190 offset:1024
	s_waitcnt lgkmcnt(9)
	v_lshlrev_b32_e32 v43, 16, v52
	v_mul_f32_e32 v42, v42, v43
	v_cvt_pk_bf16_f32 v42, v42, s0
	s_waitcnt lgkmcnt(1)
	v_sub_f32_e32 v34, v44, v34
	s_waitcnt lgkmcnt(0)
	v_mul_f32_e32 v38, v138, v38
	v_fmac_f32_e32 v38, v139, v34
	ds_write_b16 v183, v42 offset:7344
	v_mfma_f32_32x32x16_bf16 v[16:31], v[84:87], v[76:79], v[16:31]
	s_waitcnt vmcnt(0)
	v_add_f32_e32 v34, v104, v38
	v_lshlrev_b32_e32 v38, 16, v56
	v_mul_f32_e32 v34, v34, v38
	v_cvt_pk_bf16_f32 v34, v34, s0
	ds_write_b16 v183, v34 offset:8064
	v_sub_f32_e32 v34, v45, v35
	v_mul_f32_e32 v35, v138, v39
	v_fmac_f32_e32 v35, v139, v34
	v_add_f32_e32 v34, v105, v35
	v_lshlrev_b32_e32 v35, 16, v57
	v_mul_f32_e32 v34, v34, v35
	v_cvt_pk_bf16_f32 v34, v34, s0
	ds_write_b16 v183, v34 offset:8208
	v_sub_f32_e32 v34, v46, v36
	v_mul_f32_e32 v35, v138, v40
	v_fmac_f32_e32 v35, v139, v34
	v_add_f32_e32 v34, v106, v35
	v_lshlrev_b32_e32 v35, 16, v58
	v_mul_f32_e32 v34, v34, v35
	v_cvt_pk_bf16_f32 v34, v34, s0
	ds_write_b16 v183, v34 offset:8352
	v_sub_f32_e32 v34, v47, v37
	v_mul_f32_e32 v35, v138, v41
	v_fmac_f32_e32 v35, v139, v34
	v_add_f32_e32 v34, v107, v35
	v_lshlrev_b32_e32 v35, 16, v59
	v_mul_f32_e32 v34, v34, v35
	v_cvt_pk_bf16_f32 v34, v34, s0
	ds_write_b16 v183, v34 offset:8496
	global_load_dword v34, v[170:171], off offset:128
	global_load_dword v35, v[136:137], off offset:128
	global_load_dword v56, v[134:135], off
	global_load_dwordx3 v[60:62], v[132:133], off offset:4
	global_load_dwordx4 v[36:39], v[132:133], off offset:32
	v_mfma_f32_32x32x16_bf16 v[16:31], v[80:83], v[68:71], v[16:31]
	ds_read_b128 v[40:43], v182 offset:1536
	ds_read_b128 v[44:47], v182 offset:1024
	global_load_dwordx4 v[52:55], v[132:133], off offset:64
	v_mfma_f32_32x32x16_bf16 v[0:15], v[88:91], v[96:99], v[0:15]
	s_waitcnt lgkmcnt(1)
	s_nop 6
	v_sub_f32_e32 v16, v16, v40
	s_waitcnt vmcnt(5) lgkmcnt(0)
	v_mul_f32_e32 v40, v34, v44
	ds_read_u16 v44, v183 offset:64
	s_waitcnt vmcnt(4)
	v_fmac_f32_e32 v40, v35, v16
	s_waitcnt vmcnt(3)
	v_add_f32_e32 v16, v56, v40
	ds_read_b128 v[56:59], v184 offset:1024
	v_mfma_f32_32x32x16_bf16 v[0:15], v[72:75], v[76:79], v[0:15]
	s_waitcnt lgkmcnt(1)
	v_lshlrev_b32_e32 v40, 16, v44
	v_mul_f32_e32 v16, v16, v40
	v_cvt_pk_bf16_f32 v16, v16, s0
	ds_write_b16 v183, v16 offset:64
	v_sub_f32_e32 v16, v17, v41
	v_mul_f32_e32 v16, v35, v16
	v_fmac_f32_e32 v16, v34, v45
	s_waitcnt vmcnt(2)
	v_add_f32_e32 v16, v60, v16
	ds_read_u16 v17, v193 offset:64
	ds_read_u16 v40, v193 offset:208
	ds_read_u16 v41, v193 offset:352
	ds_read_u16 v60, v193 offset:1072
	ds_read_u16 v63, v193 offset:1216
	ds_read_u16 v80, v193 offset:1360
	ds_read_u16 v81, v193 offset:1504
	ds_read_u16 v82, v193 offset:2224
	s_waitcnt lgkmcnt(7)
	v_lshlrev_b32_e32 v17, 16, v17
	v_mul_f32_e32 v16, v16, v17
	v_cvt_pk_bf16_f32 v16, v16, s0
	ds_write_b16 v193, v16 offset:64
	v_sub_f32_e32 v16, v18, v42
	v_mul_f32_e32 v16, v35, v16
	v_fmac_f32_e32 v16, v34, v46
	v_add_f32_e32 v16, v61, v16
	s_waitcnt lgkmcnt(7)
	v_lshlrev_b32_e32 v17, 16, v40
	v_mul_f32_e32 v16, v16, v17
	v_cvt_pk_bf16_f32 v16, v16, s0
	ds_write_b16 v193, v16 offset:208
	v_sub_f32_e32 v16, v19, v43
	v_mul_f32_e32 v16, v35, v16
	v_fmac_f32_e32 v16, v34, v47
	v_add_f32_e32 v16, v62, v16
	s_waitcnt lgkmcnt(7)
	v_lshlrev_b32_e32 v17, 16, v41
	v_mul_f32_e32 v40, v16, v17
	v_cvt_pk_bf16_f32 v44, v40, s0
	global_load_dwordx4 v[40:43], v[132:133], off offset:96
	ds_read_b128 v[16:19], v184 offset:1536
	ds_write_b16 v193, v44 offset:352
	ds_read_b128 v[44:47], v185 offset:1024
	v_mfma_f32_32x32x16_bf16 v[0:15], v[64:67], v[68:71], v[0:15]
	s_waitcnt lgkmcnt(2)
	v_sub_f32_e32 v16, v20, v16
	v_mul_f32_e32 v16, v35, v16
	v_fmac_f32_e32 v16, v34, v56
	s_waitcnt vmcnt(2)
	v_add_f32_e32 v16, v36, v16
	v_lshlrev_b32_e32 v20, 16, v60
	v_mul_f32_e32 v16, v16, v20
	v_cvt_pk_bf16_f32 v16, v16, s0
	ds_write_b16 v193, v16 offset:1072
	v_sub_f32_e32 v16, v21, v17
	v_mul_f32_e32 v16, v35, v16
	v_fmac_f32_e32 v16, v34, v57
	v_add_f32_e32 v16, v37, v16
	v_lshlrev_b32_e32 v17, 16, v63
	v_mul_f32_e32 v16, v16, v17
	v_cvt_pk_bf16_f32 v16, v16, s0
	ds_write_b16 v193, v16 offset:1216
	v_sub_f32_e32 v16, v22, v18
	v_mul_f32_e32 v16, v35, v16
	v_fmac_f32_e32 v16, v34, v58
	v_add_f32_e32 v16, v38, v16
	v_lshlrev_b32_e32 v17, 16, v80
	v_mul_f32_e32 v16, v16, v17
	v_cvt_pk_bf16_f32 v16, v16, s0
	ds_write_b16 v193, v16 offset:1360
	v_sub_f32_e32 v16, v23, v19
	v_mul_f32_e32 v16, v35, v16
	v_fmac_f32_e32 v16, v34, v59
	v_add_f32_e32 v20, v39, v16
	ds_read_b128 v[16:19], v185 offset:1536
	v_lshlrev_b32_e32 v21, 16, v81
	v_mul_f32_e32 v20, v20, v21
	v_cvt_pk_bf16_f32 v20, v20, s0
	ds_write_b16 v193, v20 offset:1504
	s_waitcnt lgkmcnt(1)
	v_sub_f32_e32 v16, v24, v16
	v_mul_f32_e32 v16, v35, v16
	v_fmac_f32_e32 v16, v34, v44
	s_waitcnt vmcnt(1)
	v_add_f32_e32 v16, v52, v16
	v_lshlrev_b32_e32 v24, 16, v82
	v_mul_f32_e32 v16, v16, v24
	v_cvt_pk_bf16_f32 v16, v16, s0
	ds_write_b16 v193, v16 offset:2224
	v_sub_f32_e32 v16, v25, v17
	v_mul_f32_e32 v16, v35, v16
	ds_read_b128 v[20:23], v186 offset:1024
	v_fmac_f32_e32 v16, v34, v45
	ds_read_u16 v17, v193 offset:2368
	ds_read_u16 v24, v193 offset:2512
	ds_read_u16 v25, v193 offset:2656
	ds_read_u16 v36, v193 offset:3376
	ds_read_u16 v37, v193 offset:3520
	ds_read_u16 v38, v193 offset:3664
	ds_read_u16 v39, v193 offset:3808
	v_add_f32_e32 v16, v53, v16
	s_waitcnt lgkmcnt(6)
	v_lshlrev_b32_e32 v17, 16, v17
	v_mul_f32_e32 v16, v16, v17
	v_cvt_pk_bf16_f32 v16, v16, s0
	ds_write_b16 v193, v16 offset:2368
	v_sub_f32_e32 v16, v26, v18
	v_mul_f32_e32 v16, v35, v16
	v_fmac_f32_e32 v16, v34, v46
	v_add_f32_e32 v16, v54, v16
	s_waitcnt lgkmcnt(6)
	v_lshlrev_b32_e32 v17, 16, v24
	v_mul_f32_e32 v16, v16, v17
	v_cvt_pk_bf16_f32 v16, v16, s0
	ds_write_b16 v193, v16 offset:2512
	v_sub_f32_e32 v16, v27, v19
	v_mul_f32_e32 v16, v35, v16
	v_fmac_f32_e32 v16, v34, v47
	v_add_f32_e32 v24, v55, v16
	ds_read_b128 v[16:19], v186 offset:1536
	s_waitcnt lgkmcnt(7)
	v_lshlrev_b32_e32 v25, 16, v25
	v_mul_f32_e32 v24, v24, v25
	v_cvt_pk_bf16_f32 v24, v24, s0
	ds_write_b16 v193, v24 offset:2656
	s_waitcnt lgkmcnt(1)
	v_sub_f32_e32 v16, v28, v16
	v_mul_f32_e32 v16, v35, v16
	v_fmac_f32_e32 v16, v34, v20
	v_lshlrev_b32_e32 v20, 16, v36
	s_waitcnt vmcnt(0)
	v_add_f32_e32 v16, v40, v16
	v_mul_f32_e32 v16, v16, v20
	v_cvt_pk_bf16_f32 v16, v16, s0
	ds_write_b16 v193, v16 offset:3376
	v_sub_f32_e32 v16, v29, v17
	v_mul_f32_e32 v16, v35, v16
	v_fmac_f32_e32 v16, v34, v21
	v_add_f32_e32 v16, v41, v16
	v_lshlrev_b32_e32 v17, 16, v37
	v_mul_f32_e32 v16, v16, v17
	v_cvt_pk_bf16_f32 v16, v16, s0
	ds_write_b16 v193, v16 offset:3520
	v_sub_f32_e32 v16, v30, v18
	v_mul_f32_e32 v16, v35, v16
	v_fmac_f32_e32 v16, v34, v22
	v_add_f32_e32 v16, v42, v16
	v_lshlrev_b32_e32 v17, 16, v38
	v_mul_f32_e32 v16, v16, v17
	v_cvt_pk_bf16_f32 v16, v16, s0
	ds_write_b16 v193, v16 offset:3664
	v_sub_f32_e32 v16, v31, v19
	v_mul_f32_e32 v16, v35, v16
	v_fmac_f32_e32 v16, v34, v23
	v_add_f32_e32 v16, v43, v16
	v_lshlrev_b32_e32 v17, 16, v39
	v_mul_f32_e32 v16, v16, v17
	v_cvt_pk_bf16_f32 v16, v16, s0
	ds_write_b16 v193, v16 offset:3808
	global_load_dwordx4 v[16:19], v[132:133], off offset:128
	global_load_dwordx4 v[20:23], v[48:49], off offset:128
	ds_read_b128 v[24:27], v187 offset:1536
	ds_read_b128 v[28:31], v187 offset:1024
	global_load_dwordx4 v[36:39], v[50:51], off offset:128
	s_waitcnt lgkmcnt(1)
	v_sub_f32_e32 v0, v0, v24
	s_waitcnt lgkmcnt(0)
	v_mul_f32_e32 v24, v34, v28
	v_fmac_f32_e32 v24, v35, v0
	s_waitcnt vmcnt(2)
	v_add_f32_e32 v0, v16, v24
	ds_read_u16 v16, v183 offset:4672
	ds_read_u16 v24, v183 offset:4816
	ds_read_u16 v28, v183 offset:4960
	ds_read_u16 v40, v183 offset:5104
	ds_read_u16 v41, v183 offset:5824
	ds_read_u16 v42, v183 offset:5968
	ds_read_u16 v43, v183 offset:6112
	ds_read_u16 v44, v183 offset:6256
	s_waitcnt lgkmcnt(7)
	v_lshlrev_b32_e32 v16, 16, v16
	v_mul_f32_e32 v0, v0, v16
	v_cvt_pk_bf16_f32 v0, v0, s0
	ds_write_b16 v183, v0 offset:4672
	v_sub_f32_e32 v0, v1, v25
	v_mul_f32_e32 v0, v35, v0
	v_fmac_f32_e32 v0, v34, v29
	v_add_f32_e32 v0, v17, v0
	s_waitcnt lgkmcnt(7)
	v_lshlrev_b32_e32 v1, 16, v24
	v_mul_f32_e32 v0, v0, v1
	v_cvt_pk_bf16_f32 v0, v0, s0
	ds_write_b16 v183, v0 offset:4816
	v_sub_f32_e32 v0, v2, v26
	v_mul_f32_e32 v0, v35, v0
	v_fmac_f32_e32 v0, v34, v30
	v_add_f32_e32 v0, v18, v0
	s_waitcnt lgkmcnt(7)
	v_lshlrev_b32_e32 v1, 16, v28
	v_mul_f32_e32 v0, v0, v1
	v_cvt_pk_bf16_f32 v0, v0, s0
	ds_write_b16 v183, v0 offset:4960
	v_sub_f32_e32 v0, v3, v27
	v_mul_f32_e32 v0, v35, v0
	v_fmac_f32_e32 v0, v34, v31
	v_add_f32_e32 v24, v19, v0
	s_waitcnt lgkmcnt(7)
	v_lshlrev_b32_e32 v25, 16, v40
	v_mul_f32_e32 v24, v24, v25
	v_cvt_pk_bf16_f32 v24, v24, s0
	ds_read_b128 v[0:3], v188 offset:1024
	ds_read_b128 v[16:19], v188 offset:1536
	ds_write_b16 v183, v24 offset:5104
	global_load_dwordx4 v[24:27], v[32:33], off offset:128
	s_waitcnt lgkmcnt(1)
	v_sub_f32_e32 v4, v4, v16
	v_mul_f32_e32 v4, v35, v4
	v_fmac_f32_e32 v4, v34, v0
	s_waitcnt vmcnt(2)
	v_add_f32_e32 v0, v20, v4
	v_lshlrev_b32_e32 v4, 16, v41
	v_mul_f32_e32 v0, v0, v4
	v_cvt_pk_bf16_f32 v0, v0, s0
	ds_write_b16 v183, v0 offset:5824
	v_sub_f32_e32 v0, v5, v17
	v_mul_f32_e32 v0, v35, v0
	v_fmac_f32_e32 v0, v34, v1
	v_add_f32_e32 v0, v21, v0
	v_lshlrev_b32_e32 v1, 16, v42
	v_mul_f32_e32 v0, v0, v1
	v_cvt_pk_bf16_f32 v0, v0, s0
	ds_write_b16 v183, v0 offset:5968
	v_sub_f32_e32 v0, v6, v18
	v_mul_f32_e32 v0, v35, v0
	v_fmac_f32_e32 v0, v34, v2
	v_add_f32_e32 v0, v22, v0
	v_lshlrev_b32_e32 v1, 16, v43
	v_mul_f32_e32 v0, v0, v1
	v_cvt_pk_bf16_f32 v0, v0, s0
	ds_write_b16 v183, v0 offset:6112
	v_sub_f32_e32 v0, v7, v19
	v_mul_f32_e32 v0, v35, v0
	v_fmac_f32_e32 v0, v34, v3
	v_add_f32_e32 v16, v23, v0
	ds_read_b128 v[0:3], v189 offset:1024
	ds_read_b128 v[4:7], v189 offset:1536
	v_lshlrev_b32_e32 v17, 16, v44
	v_mul_f32_e32 v16, v16, v17
	v_cvt_pk_bf16_f32 v16, v16, s0
	ds_write_b16 v183, v16 offset:6256
	s_waitcnt lgkmcnt(1)
	v_sub_f32_e32 v4, v8, v4
	v_mul_f32_e32 v4, v35, v4
	v_fmac_f32_e32 v4, v34, v0
	s_waitcnt vmcnt(1)
	v_add_f32_e32 v0, v36, v4
	ds_read_u16 v4, v183 offset:6976
	ds_read_u16 v8, v183 offset:7120
	ds_read_u16 v16, v183 offset:7264
	ds_read_u16 v17, v183 offset:7408
	ds_read_u16 v18, v183 offset:8128
	ds_read_u16 v19, v183 offset:8272
	ds_read_u16 v20, v183 offset:8416
	ds_read_u16 v21, v183 offset:8560
	s_waitcnt lgkmcnt(7)
	v_lshlrev_b32_e32 v4, 16, v4
	v_mul_f32_e32 v0, v0, v4
	v_cvt_pk_bf16_f32 v0, v0, s0
	ds_write_b16 v183, v0 offset:6976
	v_sub_f32_e32 v0, v9, v5
	v_mul_f32_e32 v0, v35, v0
	v_fmac_f32_e32 v0, v34, v1
	v_add_f32_e32 v0, v37, v0
	s_waitcnt lgkmcnt(7)
	v_lshlrev_b32_e32 v1, 16, v8
	v_mul_f32_e32 v0, v0, v1
	v_cvt_pk_bf16_f32 v0, v0, s0
	ds_write_b16 v183, v0 offset:7120
	v_sub_f32_e32 v0, v10, v6
	v_mul_f32_e32 v0, v35, v0
	v_fmac_f32_e32 v0, v34, v2
	v_add_f32_e32 v0, v38, v0
	s_waitcnt lgkmcnt(7)
	v_lshlrev_b32_e32 v1, 16, v16
	v_mul_f32_e32 v0, v0, v1
	v_cvt_pk_bf16_f32 v0, v0, s0
	ds_write_b16 v183, v0 offset:7264
	v_sub_f32_e32 v0, v11, v7
	v_mul_f32_e32 v0, v35, v0
	v_fmac_f32_e32 v0, v34, v3
	v_add_f32_e32 v8, v39, v0
	ds_read_b128 v[0:3], v190 offset:1024
	ds_read_b128 v[4:7], v190 offset:1536
	s_waitcnt lgkmcnt(9)
	v_lshlrev_b32_e32 v9, 16, v17
	v_mul_f32_e32 v8, v8, v9
	v_cvt_pk_bf16_f32 v8, v8, s0
	ds_write_b16 v183, v8 offset:7408
	s_waitcnt lgkmcnt(1)
	v_sub_f32_e32 v4, v12, v4
	v_mul_f32_e32 v4, v35, v4
	v_fmac_f32_e32 v4, v34, v0
	s_waitcnt vmcnt(0)
	v_add_f32_e32 v0, v24, v4
	v_lshlrev_b32_e32 v4, 16, v18
	v_mul_f32_e32 v0, v0, v4
	v_cvt_pk_bf16_f32 v0, v0, s0
	ds_write_b16 v183, v0 offset:8128
	v_sub_f32_e32 v0, v13, v5
	v_mul_f32_e32 v0, v35, v0
	v_fmac_f32_e32 v0, v34, v1
	v_add_f32_e32 v0, v25, v0
	v_lshlrev_b32_e32 v1, 16, v19
	v_mul_f32_e32 v0, v0, v1
	v_cvt_pk_bf16_f32 v0, v0, s0
	ds_write_b16 v183, v0 offset:8272
	v_sub_f32_e32 v0, v14, v6
	v_mul_f32_e32 v0, v35, v0
	v_fmac_f32_e32 v0, v34, v2
	v_add_f32_e32 v0, v26, v0
	v_lshlrev_b32_e32 v1, 16, v20
	v_mul_f32_e32 v0, v0, v1
	v_cvt_pk_bf16_f32 v0, v0, s0
	ds_write_b16 v183, v0 offset:8416
	v_sub_f32_e32 v0, v15, v7
	v_mul_f32_e32 v0, v35, v0
	v_fmac_f32_e32 v0, v34, v3
	v_add_f32_e32 v0, v27, v0
	v_lshlrev_b32_e32 v1, 16, v21
	v_mul_f32_e32 v0, v0, v1
	v_cvt_pk_bf16_f32 v0, v0, s0
	ds_write_b16 v183, v0 offset:8560
	s_waitcnt lgkmcnt(0)
	v_mov_b32_e32 v0, v192

.LBB0_1563:
	s_ashr_i32 s10, s26, 4
	s_and_b32 s14, s26, 7
	s_and_b32 s15, s10, 0x7ffffff8
	s_or_b32 s14, s15, s14
	s_lshl_b32 s14, s14, 1
	s_bfe_u32 s15, s26, 0x10006
	s_or_b32 s14, s14, s15
	s_lshl_b32 s16, s26, 4
	s_and_b32 s16, s16, 0x380
	v_add_u32_e32 v248, s16, v148
	v_ashrrev_i32_e32 v249, 31, v248
	v_lshlrev_b64 v[248:249], 9, v[248:249]
	v_lshl_add_u64 v[248:249], v[164:165], 0, v[248:249]
	global_load_dwordx4 v[96:99], v[248:249], off
	global_load_dwordx4 v[100:103], v[248:249], off offset:16
	global_load_dwordx4 v[104:107], v[248:249], off offset:32
	global_load_dwordx4 v[108:111], v[248:249], off offset:48
	global_load_dwordx4 v[112:115], v[248:249], off offset:64
	global_load_dwordx4 v[116:119], v[248:249], off offset:80
	global_load_dwordx4 v[120:123], v[248:249], off offset:96
	global_load_dwordx4 v[124:127], v[248:249], off offset:112
	s_lshr_b32 s17, s26, 3
	s_and_b32 s17, s17, 7
	s_lshl_b32 s16, s14, 11
	s_lshl_b32 s18, s17, 8
	s_or_b32 s16, s16, s18
	v_ashrrev_i32_e32 v250, 4, v153
	v_add_u32_e32 v250, s16, v250
	v_mov_b32_e32 v251, 0
	v_lshlrev_b64 v[250:251], 8, v[250:251]
	v_lshl_add_u64 v[250:251], v[150:151], 0, v[250:251]
	s_movk_i32 s18, 0x2000
	s_mov_b32 s19, 0
	global_load_dwordx4 v[64:67], v[250:251], off
	v_lshl_add_u64 v[250:251], v[250:251], 0, s[18:19]
	global_load_dwordx4 v[68:71], v[250:251], off
	v_lshl_add_u64 v[250:251], v[250:251], 0, s[18:19]
	global_load_dwordx4 v[72:75], v[250:251], off
	v_lshl_add_u64 v[250:251], v[250:251], 0, s[18:19]
	global_load_dwordx4 v[76:79], v[250:251], off
	v_lshl_add_u64 v[250:251], v[250:251], 0, s[18:19]
	global_load_dwordx4 v[80:83], v[250:251], off
	v_lshl_add_u64 v[250:251], v[250:251], 0, s[18:19]
	global_load_dwordx4 v[84:87], v[250:251], off
	v_lshl_add_u64 v[250:251], v[250:251], 0, s[18:19]
	global_load_dwordx4 v[88:91], v[250:251], off
	v_lshl_add_u64 v[250:251], v[250:251], 0, s[18:19]
	global_load_dwordx4 v[92:95], v[250:251], off
	v_lshl_add_u32 v248, s14, 7, v178
	v_ashrrev_i32_e32 v249, 31, v248
	v_lshlrev_b64 v[248:249], 12, v[248:249]
	v_lshl_or_b32 v248, s17, 9, v248
	v_lshl_add_u64 v[248:249], v[166:167], 0, v[248:249]
	s_mov_b32 s18, 0x6000000
	v_lshl_add_u64 v[248:249], v[248:249], 0, s[18:19]
	s_mov_b32 s18, 0x8000
	global_load_dwordx4 v[216:219], v[248:249], off
	v_lshl_add_u64 v[248:249], v[248:249], 0, s[18:19]
	global_load_dwordx4 v[220:223], v[248:249], off
	v_lshl_add_u64 v[248:249], v[248:249], 0, s[18:19]
	global_load_dwordx4 v[224:227], v[248:249], off
	v_lshl_add_u64 v[248:249], v[248:249], 0, s[18:19]
	global_load_dwordx4 v[228:231], v[248:249], off
	v_lshl_add_u64 v[248:249], v[248:249], 0, s[18:19]
	global_load_dwordx4 v[232:235], v[248:249], off
	v_lshl_add_u64 v[248:249], v[248:249], 0, s[18:19]
	global_load_dwordx4 v[236:239], v[248:249], off
	v_lshl_add_u64 v[248:249], v[248:249], 0, s[18:19]
	global_load_dwordx4 v[240:243], v[248:249], off
	v_lshl_add_u64 v[248:249], v[248:249], 0, s[18:19]
	global_load_dwordx4 v[244:247], v[248:249], off
	s_waitcnt vmcnt(63) expcnt(7) lgkmcnt(15)
	s_barrier
	s_and_saveexec_b64 s[16:17], s[0:1]
	s_cbranch_execz .LBB0_1565
	v_lshl_add_u32 v0, s14, 7, v153
	v_ashrrev_i32_e32 v1, 31, v0
	v_lshlrev_b64 v[0:1], 8, v[0:1]
	v_lshl_add_u64 v[60:61], s[8:9], 0, v[0:1]
	global_load_dwordx4 v[0:3], v[60:61], off
	global_load_dwordx4 v[4:7], v[60:61], off offset:16
	global_load_dwordx4 v[8:11], v[60:61], off offset:32
	global_load_dwordx4 v[12:15], v[60:61], off offset:48
	global_load_dwordx4 v[16:19], v[60:61], off offset:64
	global_load_dwordx4 v[20:23], v[60:61], off offset:80
	global_load_dwordx4 v[24:27], v[60:61], off offset:96
	global_load_dwordx4 v[28:31], v[60:61], off offset:112
	global_load_dwordx4 v[32:35], v[60:61], off offset:128
	global_load_dwordx4 v[36:39], v[60:61], off offset:144
	global_load_dwordx4 v[40:43], v[60:61], off offset:160
	global_load_dwordx4 v[44:47], v[60:61], off offset:176
	global_load_dwordx4 v[48:51], v[60:61], off offset:192
	global_load_dwordx4 v[52:55], v[60:61], off offset:208
	global_load_dwordx4 v[56:59], v[60:61], off offset:224
	s_nop 0
	global_load_dwordx4 v[60:63], v[60:61], off offset:240
	s_waitcnt vmcnt(15)
	v_pk_add_f32 v[0:1], v[0:1], 0 op_sel_hi:[1,0]
	s_nop 0
	v_pk_add_f32 v[0:1], v[0:1], v[2:3]
	s_waitcnt vmcnt(14)
	v_pk_add_f32 v[0:1], v[0:1], v[4:5]
	s_nop 0
	v_pk_add_f32 v[0:1], v[0:1], v[6:7]
	s_waitcnt vmcnt(13)
	v_pk_add_f32 v[0:1], v[0:1], v[8:9]
	s_nop 0
	v_pk_add_f32 v[0:1], v[0:1], v[10:11]
	s_waitcnt vmcnt(12)
	v_pk_add_f32 v[0:1], v[0:1], v[12:13]
	s_nop 0
	v_pk_add_f32 v[0:1], v[0:1], v[14:15]
	s_waitcnt vmcnt(11)
	v_pk_add_f32 v[0:1], v[0:1], v[16:17]
	s_nop 0
	v_pk_add_f32 v[0:1], v[0:1], v[18:19]
	s_waitcnt vmcnt(10)
	v_pk_add_f32 v[0:1], v[0:1], v[20:21]
	s_nop 0
	v_pk_add_f32 v[0:1], v[0:1], v[22:23]
	s_waitcnt vmcnt(9)
	v_pk_add_f32 v[0:1], v[0:1], v[24:25]
	s_nop 0
	v_pk_add_f32 v[0:1], v[0:1], v[26:27]
	s_waitcnt vmcnt(8)
	v_pk_add_f32 v[0:1], v[0:1], v[28:29]
	s_nop 0
	v_pk_add_f32 v[0:1], v[0:1], v[30:31]
	s_waitcnt vmcnt(7)
	v_pk_add_f32 v[0:1], v[0:1], v[32:33]
	s_nop 0
	v_pk_add_f32 v[0:1], v[0:1], v[34:35]
	s_waitcnt vmcnt(6)
	v_pk_add_f32 v[0:1], v[0:1], v[36:37]
	s_nop 0
	v_pk_add_f32 v[0:1], v[0:1], v[38:39]
	s_waitcnt vmcnt(5)
	v_pk_add_f32 v[0:1], v[0:1], v[40:41]
	s_nop 0
	v_pk_add_f32 v[0:1], v[0:1], v[42:43]
	s_waitcnt vmcnt(4)
	v_pk_add_f32 v[0:1], v[0:1], v[44:45]
	s_nop 0
	v_pk_add_f32 v[0:1], v[0:1], v[46:47]
	s_waitcnt vmcnt(3)
	v_pk_add_f32 v[0:1], v[0:1], v[48:49]
	s_nop 0
	v_pk_add_f32 v[0:1], v[0:1], v[50:51]
	s_waitcnt vmcnt(2)
	v_pk_add_f32 v[0:1], v[0:1], v[52:53]
	s_nop 0
	v_pk_add_f32 v[0:1], v[0:1], v[54:55]
	s_waitcnt vmcnt(1)
	v_pk_add_f32 v[0:1], v[0:1], v[56:57]
	s_nop 0
	v_pk_add_f32 v[0:1], v[0:1], v[58:59]
	s_waitcnt vmcnt(0)
	v_pk_add_f32 v[0:1], v[0:1], v[60:61]
	s_nop 0
	v_pk_add_f32 v[0:1], v[0:1], v[62:63]
	s_nop 0
	v_pk_mul_f32 v[0:1], v[0:1], s[12:13] op_sel_hi:[1,0]
	s_nop 0
	v_fma_f32 v1, -v0, v0, v1
	v_max_f32_e32 v1, 0, v1
	v_add_f32_e32 v1, 0x358637bd, v1
	v_mul_f32_e32 v2, 0x4b800000, v1
	v_cmp_gt_f32_e32 vcc, s22, v1
	s_nop 1
	v_cndmask_b32_e32 v1, v1, v2, vcc
	v_rsq_f32_e32 v1, v1
	s_nop 0
	v_mul_f32_e32 v2, 0x45800000, v1
	v_cndmask_b32_e32 v1, v1, v2, vcc
	ds_write2st64_b32 v172, v0, v1 offset1:2
.LBB0_1565:
	s_or_b64 exec, exec, s[16:17]
	s_lshl_b32 s16, s26, 4
	s_and_b32 s16, s16, 0x380
	v_add_u32_e32 v0, s16, v148
	v_ashrrev_i32_e32 v1, 31, v0
	v_lshlrev_b64 v[0:1], 9, v[0:1]
	v_mov_b32_e32 v10, 0
	s_lshr_b32 s27, s26, 6
	s_lshr_b32 s15, s26, 3
	v_lshl_add_u64 v[8:9], v[164:165], 0, v[0:1]
	s_mov_b64 s[16:17], 0
	v_mov_b32_e32 v7, v191
	v_mov_b32_e32 v16, v173
	v_mov_b32_e32 v17, v174
	v_mov_b32_e32 v11, v10
	s_waitcnt lgkmcnt(0)
	s_barrier
	s_waitcnt vmcnt(0)
	v_cmp_le_i32_e32 vcc, v16, v148
	v_mov_b32_e32 v0, v97
	v_mov_b32_e32 v1, v98
	v_mov_b32_e32 v2, v99
	v_mov_b32_e32 v3, v100
	v_mov_b32_e32 v4, v101
	v_mov_b32_e32 v5, v102
	v_mov_b32_e32 v6, v103
	v_cndmask_b32_e32 v12, 0, v96, vcc
	ds_read2st64_b64 v[18:21], v7 offset1:1
	v_cmp_lt_i32_e32 vcc, v16, v148
	s_add_u32 s16, s16, 32
	s_addc_u32 s17, s17, 0
	s_waitcnt vmcnt(0)
	v_cndmask_b32_e32 v13, 0, v0, vcc
	s_waitcnt lgkmcnt(0)
	v_pk_mul_f32 v[14:15], v[12:13], v[20:21]
	s_cmpk_eq_i32 s16, 0x80
	v_cvt_pk_bf16_f32 v0, v14, v15
	v_and_b32_e32 v32, 0xffff0000, v0
	v_lshlrev_b32_e32 v33, 16, v0
	v_or_b32_e32 v0, 3, v16
	v_or_b32_e32 v14, 2, v16
	v_cmp_le_i32_e32 vcc, v0, v149
	v_mul_f32_e32 v15, v18, v33
	v_lshl_add_u32 v18, v14, 2, s3
	v_cndmask_b32_e32 v21, 0, v2, vcc
	v_cmp_le_i32_e32 vcc, v14, v148
	v_lshl_add_u32 v22, v0, 2, s3
	v_or_b32_e32 v2, 4, v16
	v_cndmask_b32_e32 v20, 0, v1, vcc
	ds_read_b64 v[0:1], v18 offset:512
	v_lshl_add_u32 v14, v2, 2, s3
	ds_read_b32 v18, v18
	ds_read_b32 v22, v22
	ds_read_b32 v28, v14
	v_mul_f32_e32 v19, v19, v32
	v_add_u32_e32 v7, 32, v7
	s_waitcnt lgkmcnt(3)
	v_pk_mul_f32 v[0:1], v[20:21], v[0:1]
	s_nop 0
	v_cvt_pk_bf16_f32 v0, v0, v1
	v_and_b32_e32 v34, 0xffff0000, v0
	v_lshlrev_b32_e32 v35, 16, v0
	v_or_b32_e32 v0, 5, v16
	v_cmp_le_i32_e32 vcc, v0, v149
	s_waitcnt lgkmcnt(2)
	v_mul_f32_e32 v1, v18, v35
	v_lshl_add_u32 v18, v0, 2, s3
	v_cndmask_b32_e32 v25, 0, v4, vcc
	v_cmp_le_i32_e32 vcc, v2, v148
	v_or_b32_e32 v0, 6, v16
	v_lshl_add_u32 v4, v0, 2, s3
	v_cndmask_b32_e32 v24, 0, v3, vcc
	ds_read_b64 v[2:3], v14 offset:512
	ds_read_b32 v14, v18
	ds_read_b32 v18, v4
	ds_read_b64 v[26:27], v4 offset:512
	s_waitcnt lgkmcnt(5)
	v_mul_f32_e32 v23, v22, v34
	v_mov_b32_e32 v22, v21
	s_waitcnt lgkmcnt(3)
	v_pk_mul_f32 v[2:3], v[24:25], v[2:3]
	s_nop 0
	v_cvt_pk_bf16_f32 v2, v2, v3
	v_and_b32_e32 v36, 0xffff0000, v2
	v_lshlrev_b32_e32 v37, 16, v2
	v_or_b32_e32 v2, 7, v16
	v_cmp_le_i32_e32 vcc, v2, v149
	s_waitcnt lgkmcnt(2)
	v_mul_f32_e32 v29, v14, v36
	v_mov_b32_e32 v14, v12
	v_cndmask_b32_e32 v31, 0, v6, vcc
	v_cmp_le_i32_e32 vcc, v0, v148
	v_pk_add_f32 v[10:11], v[10:11], v[14:15]
	v_mul_f32_e32 v3, v28, v37
	v_cndmask_b32_e32 v30, 0, v5, vcc
	s_waitcnt lgkmcnt(0)
	v_pk_mul_f32 v[4:5], v[30:31], v[26:27]
	v_lshl_add_u32 v28, v2, 2, s3
	v_cvt_pk_bf16_f32 v0, v4, v5
	v_lshlrev_b32_e32 v26, 16, v0
	v_mul_f32_e32 v5, v18, v26
	v_mov_b32_e32 v18, v13
	v_and_b32_e32 v6, 0xffff0000, v0
	v_pk_add_f32 v[10:11], v[18:19], v[10:11]
	v_mov_b32_e32 v0, v20
	v_pk_add_f32 v[0:1], v[0:1], v[10:11]
	v_mov_b32_e32 v2, v24
	v_pk_add_f32 v[0:1], v[22:23], v[0:1]
	v_mov_b32_e32 v4, v30
	v_pk_add_f32 v[0:1], v[2:3], v[0:1]
	ds_read_b32 v2, v28
	v_mov_b32_e32 v28, v25
	v_pk_add_f32 v[0:1], v[28:29], v[0:1]
	v_add_u32_e32 v16, 8, v16
	v_pk_add_f32 v[0:1], v[4:5], v[0:1]
	s_waitcnt lgkmcnt(0)
	v_mul_f32_e32 v3, v2, v6
	v_mov_b32_e32 v2, v31
	v_pk_add_f32 v[10:11], v[2:3], v[0:1]
	v_cvt_pk_bf16_f32 v0, v33, v32
	v_cvt_pk_bf16_f32 v1, v35, v34
	v_cvt_pk_bf16_f32 v2, v37, v36
	v_cvt_pk_bf16_f32 v3, v26, v6
	ds_write_b128 v17, v[0:3]
	v_add_u32_e32 v17, 16, v17
	v_cmp_le_i32_e32 vcc, v16, v148
	v_mov_b32_e32 v0, v105
	v_mov_b32_e32 v1, v106
	v_mov_b32_e32 v2, v107
	v_mov_b32_e32 v3, v108
	v_mov_b32_e32 v4, v109
	v_mov_b32_e32 v5, v110
	v_mov_b32_e32 v6, v111
	v_cndmask_b32_e32 v12, 0, v104, vcc
	ds_read2st64_b64 v[18:21], v7 offset1:1
	v_cmp_lt_i32_e32 vcc, v16, v148
	s_add_u32 s16, s16, 32
	s_addc_u32 s17, s17, 0
	s_waitcnt vmcnt(0)
	v_cndmask_b32_e32 v13, 0, v0, vcc
	s_waitcnt lgkmcnt(0)
	v_pk_mul_f32 v[14:15], v[12:13], v[20:21]
	s_cmpk_eq_i32 s16, 0x80
	v_cvt_pk_bf16_f32 v0, v14, v15
	v_and_b32_e32 v32, 0xffff0000, v0
	v_lshlrev_b32_e32 v33, 16, v0
	v_or_b32_e32 v0, 3, v16
	v_or_b32_e32 v14, 2, v16
	v_cmp_le_i32_e32 vcc, v0, v149
	v_mul_f32_e32 v15, v18, v33
	v_lshl_add_u32 v18, v14, 2, s3
	v_cndmask_b32_e32 v21, 0, v2, vcc
	v_cmp_le_i32_e32 vcc, v14, v148
	v_lshl_add_u32 v22, v0, 2, s3
	v_or_b32_e32 v2, 4, v16
	v_cndmask_b32_e32 v20, 0, v1, vcc
	ds_read_b64 v[0:1], v18 offset:512
	v_lshl_add_u32 v14, v2, 2, s3
	ds_read_b32 v18, v18
	ds_read_b32 v22, v22
	ds_read_b32 v28, v14
	v_mul_f32_e32 v19, v19, v32
	v_add_u32_e32 v7, 32, v7
	s_waitcnt lgkmcnt(3)
	v_pk_mul_f32 v[0:1], v[20:21], v[0:1]
	s_nop 0
	v_cvt_pk_bf16_f32 v0, v0, v1
	v_and_b32_e32 v34, 0xffff0000, v0
	v_lshlrev_b32_e32 v35, 16, v0
	v_or_b32_e32 v0, 5, v16
	v_cmp_le_i32_e32 vcc, v0, v149
	s_waitcnt lgkmcnt(2)
	v_mul_f32_e32 v1, v18, v35
	v_lshl_add_u32 v18, v0, 2, s3
	v_cndmask_b32_e32 v25, 0, v4, vcc
	v_cmp_le_i32_e32 vcc, v2, v148
	v_or_b32_e32 v0, 6, v16
	v_lshl_add_u32 v4, v0, 2, s3
	v_cndmask_b32_e32 v24, 0, v3, vcc
	ds_read_b64 v[2:3], v14 offset:512
	ds_read_b32 v14, v18
	ds_read_b32 v18, v4
	ds_read_b64 v[26:27], v4 offset:512
	s_waitcnt lgkmcnt(5)
	v_mul_f32_e32 v23, v22, v34
	v_mov_b32_e32 v22, v21
	s_waitcnt lgkmcnt(3)
	v_pk_mul_f32 v[2:3], v[24:25], v[2:3]
	s_nop 0
	v_cvt_pk_bf16_f32 v2, v2, v3
	v_and_b32_e32 v36, 0xffff0000, v2
	v_lshlrev_b32_e32 v37, 16, v2
	v_or_b32_e32 v2, 7, v16
	v_cmp_le_i32_e32 vcc, v2, v149
	s_waitcnt lgkmcnt(2)
	v_mul_f32_e32 v29, v14, v36
	v_mov_b32_e32 v14, v12
	v_cndmask_b32_e32 v31, 0, v6, vcc
	v_cmp_le_i32_e32 vcc, v0, v148
	v_pk_add_f32 v[10:11], v[10:11], v[14:15]
	v_mul_f32_e32 v3, v28, v37
	v_cndmask_b32_e32 v30, 0, v5, vcc
	s_waitcnt lgkmcnt(0)
	v_pk_mul_f32 v[4:5], v[30:31], v[26:27]
	v_lshl_add_u32 v28, v2, 2, s3
	v_cvt_pk_bf16_f32 v0, v4, v5
	v_lshlrev_b32_e32 v26, 16, v0
	v_mul_f32_e32 v5, v18, v26
	v_mov_b32_e32 v18, v13
	v_and_b32_e32 v6, 0xffff0000, v0
	v_pk_add_f32 v[10:11], v[18:19], v[10:11]
	v_mov_b32_e32 v0, v20
	v_pk_add_f32 v[0:1], v[0:1], v[10:11]
	v_mov_b32_e32 v2, v24
	v_pk_add_f32 v[0:1], v[22:23], v[0:1]
	v_mov_b32_e32 v4, v30
	v_pk_add_f32 v[0:1], v[2:3], v[0:1]
	ds_read_b32 v2, v28
	v_mov_b32_e32 v28, v25
	v_pk_add_f32 v[0:1], v[28:29], v[0:1]
	v_add_u32_e32 v16, 8, v16
	v_pk_add_f32 v[0:1], v[4:5], v[0:1]
	s_waitcnt lgkmcnt(0)
	v_mul_f32_e32 v3, v2, v6
	v_mov_b32_e32 v2, v31
	v_pk_add_f32 v[10:11], v[2:3], v[0:1]
	v_cvt_pk_bf16_f32 v0, v33, v32
	v_cvt_pk_bf16_f32 v1, v35, v34
	v_cvt_pk_bf16_f32 v2, v37, v36
	v_cvt_pk_bf16_f32 v3, v26, v6
	ds_write_b128 v17, v[0:3]
	v_add_u32_e32 v17, 16, v17
	v_cmp_le_i32_e32 vcc, v16, v148
	v_mov_b32_e32 v0, v113
	v_mov_b32_e32 v1, v114
	v_mov_b32_e32 v2, v115
	v_mov_b32_e32 v3, v116
	v_mov_b32_e32 v4, v117
	v_mov_b32_e32 v5, v118
	v_mov_b32_e32 v6, v119
	v_cndmask_b32_e32 v12, 0, v112, vcc
	ds_read2st64_b64 v[18:21], v7 offset1:1
	v_cmp_lt_i32_e32 vcc, v16, v148
	s_add_u32 s16, s16, 32
	s_addc_u32 s17, s17, 0
	s_waitcnt vmcnt(0)
	v_cndmask_b32_e32 v13, 0, v0, vcc
	s_waitcnt lgkmcnt(0)
	v_pk_mul_f32 v[14:15], v[12:13], v[20:21]
	s_cmpk_eq_i32 s16, 0x80
	v_cvt_pk_bf16_f32 v0, v14, v15
	v_and_b32_e32 v32, 0xffff0000, v0
	v_lshlrev_b32_e32 v33, 16, v0
	v_or_b32_e32 v0, 3, v16
	v_or_b32_e32 v14, 2, v16
	v_cmp_le_i32_e32 vcc, v0, v149
	v_mul_f32_e32 v15, v18, v33
	v_lshl_add_u32 v18, v14, 2, s3
	v_cndmask_b32_e32 v21, 0, v2, vcc
	v_cmp_le_i32_e32 vcc, v14, v148
	v_lshl_add_u32 v22, v0, 2, s3
	v_or_b32_e32 v2, 4, v16
	v_cndmask_b32_e32 v20, 0, v1, vcc
	ds_read_b64 v[0:1], v18 offset:512
	v_lshl_add_u32 v14, v2, 2, s3
	ds_read_b32 v18, v18
	ds_read_b32 v22, v22
	ds_read_b32 v28, v14
	v_mul_f32_e32 v19, v19, v32
	v_add_u32_e32 v7, 32, v7
	s_waitcnt lgkmcnt(3)
	v_pk_mul_f32 v[0:1], v[20:21], v[0:1]
	s_nop 0
	v_cvt_pk_bf16_f32 v0, v0, v1
	v_and_b32_e32 v34, 0xffff0000, v0
	v_lshlrev_b32_e32 v35, 16, v0
	v_or_b32_e32 v0, 5, v16
	v_cmp_le_i32_e32 vcc, v0, v149
	s_waitcnt lgkmcnt(2)
	v_mul_f32_e32 v1, v18, v35
	v_lshl_add_u32 v18, v0, 2, s3
	v_cndmask_b32_e32 v25, 0, v4, vcc
	v_cmp_le_i32_e32 vcc, v2, v148
	v_or_b32_e32 v0, 6, v16
	v_lshl_add_u32 v4, v0, 2, s3
	v_cndmask_b32_e32 v24, 0, v3, vcc
	ds_read_b64 v[2:3], v14 offset:512
	ds_read_b32 v14, v18
	ds_read_b32 v18, v4
	ds_read_b64 v[26:27], v4 offset:512
	s_waitcnt lgkmcnt(5)
	v_mul_f32_e32 v23, v22, v34
	v_mov_b32_e32 v22, v21
	s_waitcnt lgkmcnt(3)
	v_pk_mul_f32 v[2:3], v[24:25], v[2:3]
	s_nop 0
	v_cvt_pk_bf16_f32 v2, v2, v3
	v_and_b32_e32 v36, 0xffff0000, v2
	v_lshlrev_b32_e32 v37, 16, v2
	v_or_b32_e32 v2, 7, v16
	v_cmp_le_i32_e32 vcc, v2, v149
	s_waitcnt lgkmcnt(2)
	v_mul_f32_e32 v29, v14, v36
	v_mov_b32_e32 v14, v12
	v_cndmask_b32_e32 v31, 0, v6, vcc
	v_cmp_le_i32_e32 vcc, v0, v148
	v_pk_add_f32 v[10:11], v[10:11], v[14:15]
	v_mul_f32_e32 v3, v28, v37
	v_cndmask_b32_e32 v30, 0, v5, vcc
	s_waitcnt lgkmcnt(0)
	v_pk_mul_f32 v[4:5], v[30:31], v[26:27]
	v_lshl_add_u32 v28, v2, 2, s3
	v_cvt_pk_bf16_f32 v0, v4, v5
	v_lshlrev_b32_e32 v26, 16, v0
	v_mul_f32_e32 v5, v18, v26
	v_mov_b32_e32 v18, v13
	v_and_b32_e32 v6, 0xffff0000, v0
	v_pk_add_f32 v[10:11], v[18:19], v[10:11]
	v_mov_b32_e32 v0, v20
	v_pk_add_f32 v[0:1], v[0:1], v[10:11]
	v_mov_b32_e32 v2, v24
	v_pk_add_f32 v[0:1], v[22:23], v[0:1]
	v_mov_b32_e32 v4, v30
	v_pk_add_f32 v[0:1], v[2:3], v[0:1]
	ds_read_b32 v2, v28
	v_mov_b32_e32 v28, v25
	v_pk_add_f32 v[0:1], v[28:29], v[0:1]
	v_add_u32_e32 v16, 8, v16
	v_pk_add_f32 v[0:1], v[4:5], v[0:1]
	s_waitcnt lgkmcnt(0)
	v_mul_f32_e32 v3, v2, v6
	v_mov_b32_e32 v2, v31
	v_pk_add_f32 v[10:11], v[2:3], v[0:1]
	v_cvt_pk_bf16_f32 v0, v33, v32
	v_cvt_pk_bf16_f32 v1, v35, v34
	v_cvt_pk_bf16_f32 v2, v37, v36
	v_cvt_pk_bf16_f32 v3, v26, v6
	ds_write_b128 v17, v[0:3]
	v_add_u32_e32 v17, 16, v17
	v_cmp_le_i32_e32 vcc, v16, v148
	v_mov_b32_e32 v0, v121
	v_mov_b32_e32 v1, v122
	v_mov_b32_e32 v2, v123
	v_mov_b32_e32 v3, v124
	v_mov_b32_e32 v4, v125
	v_mov_b32_e32 v5, v126
	v_mov_b32_e32 v6, v127
	v_cndmask_b32_e32 v12, 0, v120, vcc
	ds_read2st64_b64 v[18:21], v7 offset1:1
	v_cmp_lt_i32_e32 vcc, v16, v148
	s_add_u32 s16, s16, 32
	s_addc_u32 s17, s17, 0
	s_waitcnt vmcnt(0)
	v_cndmask_b32_e32 v13, 0, v0, vcc
	s_waitcnt lgkmcnt(0)
	v_pk_mul_f32 v[14:15], v[12:13], v[20:21]
	s_cmpk_eq_i32 s16, 0x80
	v_cvt_pk_bf16_f32 v0, v14, v15
	v_and_b32_e32 v32, 0xffff0000, v0
	v_lshlrev_b32_e32 v33, 16, v0
	v_or_b32_e32 v0, 3, v16
	v_or_b32_e32 v14, 2, v16
	v_cmp_le_i32_e32 vcc, v0, v149
	v_mul_f32_e32 v15, v18, v33
	v_lshl_add_u32 v18, v14, 2, s3
	v_cndmask_b32_e32 v21, 0, v2, vcc
	v_cmp_le_i32_e32 vcc, v14, v148
	v_lshl_add_u32 v22, v0, 2, s3
	v_or_b32_e32 v2, 4, v16
	v_cndmask_b32_e32 v20, 0, v1, vcc
	ds_read_b64 v[0:1], v18 offset:512
	v_lshl_add_u32 v14, v2, 2, s3
	ds_read_b32 v18, v18
	ds_read_b32 v22, v22
	ds_read_b32 v28, v14
	v_mul_f32_e32 v19, v19, v32
	v_add_u32_e32 v7, 32, v7
	s_waitcnt lgkmcnt(3)
	v_pk_mul_f32 v[0:1], v[20:21], v[0:1]
	s_nop 0
	v_cvt_pk_bf16_f32 v0, v0, v1
	v_and_b32_e32 v34, 0xffff0000, v0
	v_lshlrev_b32_e32 v35, 16, v0
	v_or_b32_e32 v0, 5, v16
	v_cmp_le_i32_e32 vcc, v0, v149
	s_waitcnt lgkmcnt(2)
	v_mul_f32_e32 v1, v18, v35
	v_lshl_add_u32 v18, v0, 2, s3
	v_cndmask_b32_e32 v25, 0, v4, vcc
	v_cmp_le_i32_e32 vcc, v2, v148
	v_or_b32_e32 v0, 6, v16
	v_lshl_add_u32 v4, v0, 2, s3
	v_cndmask_b32_e32 v24, 0, v3, vcc
	ds_read_b64 v[2:3], v14 offset:512
	ds_read_b32 v14, v18
	ds_read_b32 v18, v4
	ds_read_b64 v[26:27], v4 offset:512
	s_waitcnt lgkmcnt(5)
	v_mul_f32_e32 v23, v22, v34
	v_mov_b32_e32 v22, v21
	s_waitcnt lgkmcnt(3)
	v_pk_mul_f32 v[2:3], v[24:25], v[2:3]
	s_nop 0
	v_cvt_pk_bf16_f32 v2, v2, v3
	v_and_b32_e32 v36, 0xffff0000, v2
	v_lshlrev_b32_e32 v37, 16, v2
	v_or_b32_e32 v2, 7, v16
	v_cmp_le_i32_e32 vcc, v2, v149
	s_waitcnt lgkmcnt(2)
	v_mul_f32_e32 v29, v14, v36
	v_mov_b32_e32 v14, v12
	v_cndmask_b32_e32 v31, 0, v6, vcc
	v_cmp_le_i32_e32 vcc, v0, v148
	v_pk_add_f32 v[10:11], v[10:11], v[14:15]
	v_mul_f32_e32 v3, v28, v37
	v_cndmask_b32_e32 v30, 0, v5, vcc
	s_waitcnt lgkmcnt(0)
	v_pk_mul_f32 v[4:5], v[30:31], v[26:27]
	v_lshl_add_u32 v28, v2, 2, s3
	v_cvt_pk_bf16_f32 v0, v4, v5
	v_lshlrev_b32_e32 v26, 16, v0
	v_mul_f32_e32 v5, v18, v26
	v_mov_b32_e32 v18, v13
	v_and_b32_e32 v6, 0xffff0000, v0
	v_pk_add_f32 v[10:11], v[18:19], v[10:11]
	v_mov_b32_e32 v0, v20
	v_pk_add_f32 v[0:1], v[0:1], v[10:11]
	v_mov_b32_e32 v2, v24
	v_pk_add_f32 v[0:1], v[22:23], v[0:1]
	v_mov_b32_e32 v4, v30
	v_pk_add_f32 v[0:1], v[2:3], v[0:1]
	ds_read_b32 v2, v28
	v_mov_b32_e32 v28, v25
	v_pk_add_f32 v[0:1], v[28:29], v[0:1]
	v_add_u32_e32 v16, 8, v16
	v_pk_add_f32 v[0:1], v[4:5], v[0:1]
	s_waitcnt lgkmcnt(0)
	v_mul_f32_e32 v3, v2, v6
	v_mov_b32_e32 v2, v31
	v_pk_add_f32 v[10:11], v[2:3], v[0:1]
	v_cvt_pk_bf16_f32 v0, v33, v32
	v_cvt_pk_bf16_f32 v1, v35, v34
	v_cvt_pk_bf16_f32 v2, v37, v36
	v_cvt_pk_bf16_f32 v3, v26, v6
	ds_write_b128 v17, v[0:3]
	v_add_u32_e32 v17, 16, v17

.LBB0_1572:
	s_waitcnt lgkmcnt(0)
	v_ashrrev_i32_e32 v250, 4, v153
	v_mul_lo_u32 v250, v250, s13
	v_add_u32_e32 v250, v250, v152
	s_lshl_b32 s20, s13, 5
	ds_write_b128 v250, v[64:67] offset:18432
	v_add_u32_e32 v250, s20, v250
	ds_write_b128 v250, v[68:71] offset:18432
	v_add_u32_e32 v250, s20, v250
	ds_write_b128 v250, v[72:75] offset:18432
	v_add_u32_e32 v250, s20, v250
	ds_write_b128 v250, v[76:79] offset:18432
	v_add_u32_e32 v250, s20, v250
	ds_write_b128 v250, v[80:83] offset:18432
	v_add_u32_e32 v250, s20, v250
	ds_write_b128 v250, v[84:87] offset:18432
	v_add_u32_e32 v250, s20, v250
	ds_write_b128 v250, v[88:91] offset:18432
	v_add_u32_e32 v250, s20, v250
	ds_write_b128 v250, v[92:95] offset:18432
	s_movk_i32 s18, 0x1000
	s_waitcnt lgkmcnt(0)
	s_barrier
	ds_read_b128 v[0:3], v154
	ds_read_b128 v[8:11], v155 offset:18432
	ds_read_b128 v[136:139], v154 offset:32
	ds_read_b128 v[12:15], v155 offset:18464
	ds_read_b128 v[4:7], v154 offset:4608
	ds_read_b128 v[132:135], v154 offset:4640
	s_waitcnt lgkmcnt(4)
	v_mfma_f32_32x32x16_bf16 v[48:63], v[0:3], v[8:11], 0
	s_and_b32 s14, s23, 7
	s_lshl_b32 s10, s10, 1
	s_lshl_b32 s14, s14, 1
	s_and_b32 s10, s10, 0x1fffff0
	s_and_b32 s15, s27, 1
	s_or_b32 s10, s10, s14
	s_or_b32 s10, s10, s15
	s_waitcnt lgkmcnt(1)
	v_mfma_f32_32x32x16_bf16 v[32:47], v[4:7], v[8:11], 0
	s_mov_b64 s[14:15], 0
	v_mfma_f32_32x32x16_bf16 v[48:63], v[136:139], v[12:15], v[48:63]
	s_waitcnt lgkmcnt(0)
	v_mfma_f32_32x32x16_bf16 v[32:47], v[132:135], v[12:15], v[32:47]
	ds_read_b128 v[128:131], v154 offset:64
	ds_read_b128 v[8:11], v155 offset:18496
	ds_read_b128 v[116:119], v154 offset:96
	ds_read_b128 v[12:15], v155 offset:18528
	ds_read_b128 v[124:127], v154 offset:4672
	ds_read_b128 v[112:115], v154 offset:4704
	s_waitcnt lgkmcnt(4)
	v_mfma_f32_32x32x16_bf16 v[48:63], v[128:131], v[8:11], v[48:63]
	s_waitcnt lgkmcnt(1)
	v_mfma_f32_32x32x16_bf16 v[32:47], v[124:127], v[8:11], v[32:47]
	v_mfma_f32_32x32x16_bf16 v[48:63], v[116:119], v[12:15], v[48:63]
	s_waitcnt lgkmcnt(0)
	v_mfma_f32_32x32x16_bf16 v[32:47], v[112:115], v[12:15], v[32:47]
	ds_read_b128 v[108:111], v154 offset:55296
	ds_read_b128 v[8:11], v180
	ds_read_b128 v[12:15], v180 offset:32
	ds_read_b128 v[92:95], v154 offset:55328
	ds_read_b128 v[100:103], v154 offset:59904
	ds_read_b128 v[88:91], v154 offset:59936
	ds_read_b128 v[84:87], v154 offset:55360
	s_waitcnt lgkmcnt(5)
	v_mfma_f32_32x32x16_bf16 v[48:63], v[108:111], v[8:11], v[48:63]
	s_waitcnt lgkmcnt(2)
	v_mfma_f32_32x32x16_bf16 v[32:47], v[100:103], v[8:11], v[32:47]
	v_mfma_f32_32x32x16_bf16 v[48:63], v[92:95], v[12:15], v[48:63]
	s_waitcnt lgkmcnt(1)
	v_mfma_f32_32x32x16_bf16 v[32:47], v[88:91], v[12:15], v[32:47]
	ds_read_b128 v[12:15], v180 offset:64
	ds_read_b128 v[72:75], v154 offset:59968
	ds_read_b128 v[80:83], v154 offset:55392
	ds_read_b128 v[16:19], v180 offset:96
	ds_read_b128 v[8:11], v155 offset:23040
	ds_read_b128 v[144:147], v155 offset:23072
	ds_read_b128 v[140:143], v155 offset:23104
	ds_read_b128 v[120:123], v155 offset:23136
	ds_read_b128 v[104:107], v180 offset:4608
	ds_read_b128 v[96:99], v180 offset:4640
	ds_read_b128 v[64:67], v154 offset:60000
	ds_read_b128 v[76:79], v180 offset:4672
	ds_read_b128 v[68:71], v180 offset:4704
	s_waitcnt lgkmcnt(0)
	s_barrier
	v_mfma_f32_32x32x16_bf16 v[48:63], v[84:87], v[12:15], v[48:63]
	v_mfma_f32_32x32x16_bf16 v[32:47], v[72:75], v[12:15], v[32:47]
	v_lshl_add_u32 v12, s10, 7, v178
	v_ashrrev_i32_e32 v13, 31, v12
	v_lshlrev_b64 v[12:13], 12, v[12:13]
	v_lshl_or_b32 v12, s16, 9, v12
	v_lshl_add_u64 v[168:169], v[166:167], 0, v[12:13]
	v_mov_b32_e32 v12, v192
	v_mfma_f32_32x32x16_bf16 v[48:63], v[80:83], v[16:19], v[48:63]
	v_mfma_f32_32x32x16_bf16 v[32:47], v[64:67], v[16:19], v[32:47]
.LBB0_1574:
	s_waitcnt vmcnt(0)
	ds_write_b128 v192, v[216:219]
	ds_write_b128 v192, v[220:223] offset:1152
	ds_write_b128 v192, v[224:227] offset:2304
	ds_write_b128 v192, v[228:231] offset:3456
	ds_write_b128 v192, v[232:235] offset:4608
	ds_write_b128 v192, v[236:239] offset:5760
	ds_write_b128 v192, v[240:243] offset:6912
	ds_write_b128 v192, v[244:247] offset:8064
	v_mfma_f32_32x32x16_bf16 v[16:31], v[0:3], v[8:11], 0
	v_add_u32_e32 v170, s17, v179
	v_ashrrev_i32_e32 v171, 31, v170
	v_lshlrev_b64 v[194:195], 2, v[170:171]
	v_lshl_add_u64 v[170:171], s[24:25], 0, v[194:195]
	s_lshl_b32 s10, s16, 7
	s_waitcnt lgkmcnt(0)
	s_mov_b64 s[14:15], 0
	v_mfma_f32_32x32x16_bf16 v[0:15], v[4:7], v[8:11], 0
	v_mfma_f32_32x32x16_bf16 v[16:31], v[136:139], v[144:147], v[16:31]
	global_load_dword v138, v[170:171], off
	v_lshl_add_u64 v[136:137], s[54:55], 0, v[194:195]
	v_add_u32_e32 v194, s10, v156
	global_load_dword v139, v[136:137], off
	v_ashrrev_i32_e32 v195, 31, v194
	v_mfma_f32_32x32x16_bf16 v[0:15], v[132:135], v[144:147], v[0:15]
	v_lshl_add_u64 v[134:135], v[194:195], 2, s[28:29]
	v_lshl_add_u64 v[132:133], s[10:11], 0, v[156:157]
	v_lshl_add_u64 v[132:133], v[132:133], 2, s[28:29]
	global_load_dword v213, v[134:135], off
	global_load_dwordx3 v[210:212], v[132:133], off offset:4
	v_mfma_f32_32x32x16_bf16 v[16:31], v[128:131], v[140:143], v[16:31]
	global_load_dwordx4 v[128:131], v[132:133], off offset:32
	ds_read_b128 v[144:147], v182 offset:1536
	ds_read_b128 v[194:197], v182 offset:1024
	s_waitcnt lgkmcnt(1)
	v_sub_f32_e32 v48, v48, v144
	v_sub_f32_e32 v49, v49, v145
	v_mfma_f32_32x32x16_bf16 v[0:15], v[124:127], v[140:143], v[0:15]
	ds_read_u16 v214, v183
	ds_read_b128 v[124:127], v184 offset:1024
	ds_read_b128 v[140:143], v184 offset:1536
	ds_read_b128 v[198:201], v185 offset:1024
	global_load_dwordx4 v[202:205], v[132:133], off offset:64
	global_load_dwordx4 v[206:209], v[132:133], off offset:96
	s_waitcnt lgkmcnt(3)
	v_lshlrev_b32_e32 v144, 16, v214
	v_sub_f32_e32 v50, v50, v146
	v_sub_f32_e32 v51, v51, v147
	s_waitcnt lgkmcnt(1)
	v_sub_f32_e32 v52, v52, v140
	v_sub_f32_e32 v53, v53, v141
	v_mfma_f32_32x32x16_bf16 v[0:15], v[112:115], v[120:123], v[0:15]
	v_sub_f32_e32 v54, v54, v142
	v_sub_f32_e32 v55, v55, v143
	s_waitcnt vmcnt(6)
	v_mul_f32_e32 v112, v138, v194
	v_mfma_f32_32x32x16_bf16 v[16:31], v[116:119], v[120:123], v[16:31]
	v_mul_f32_e32 v113, v138, v195
	s_waitcnt vmcnt(5)
	v_fmac_f32_e32 v112, v139, v48
	v_mul_f32_e32 v114, v138, v196
	v_mul_f32_e32 v115, v138, v197
	v_mul_f32_e32 v116, v138, v124
	v_mul_f32_e32 v117, v138, v125
	v_mul_f32_e32 v118, v138, v126
	v_fmac_f32_e32 v113, v139, v49
	s_waitcnt vmcnt(4)
	v_add_f32_e32 v48, v213, v112
	v_mul_f32_e32 v48, v48, v144
	v_cvt_pk_bf16_f32 v48, v48, s0
	v_fmac_f32_e32 v114, v139, v50
	v_fmac_f32_e32 v115, v139, v51
	v_fmac_f32_e32 v116, v139, v52
	v_fmac_f32_e32 v117, v139, v53
	v_fmac_f32_e32 v118, v139, v54
	ds_write_b16 v183, v48
	s_waitcnt vmcnt(3)
	v_add_f32_e32 v49, v210, v113
	v_add_f32_e32 v50, v211, v114
	v_add_f32_e32 v51, v212, v115
	s_waitcnt vmcnt(2)
	v_add_f32_e32 v52, v128, v116
	v_add_f32_e32 v53, v129, v117
	v_add_f32_e32 v54, v130, v118
	ds_read_u16 v48, v193
	ds_read_u16 v112, v193 offset:144
	ds_read_u16 v113, v193 offset:288
	ds_read_u16 v114, v193 offset:1008
	ds_read_u16 v115, v193 offset:1152
	ds_read_u16 v116, v193 offset:1296
	ds_read_u16 v117, v193 offset:1440
	ds_read_u16 v118, v193 offset:2160
	s_waitcnt lgkmcnt(7)
	v_lshlrev_b32_e32 v48, 16, v48
	s_waitcnt lgkmcnt(6)
	v_lshlrev_b32_e32 v112, 16, v112
	s_waitcnt lgkmcnt(5)
	v_lshlrev_b32_e32 v113, 16, v113
	s_waitcnt lgkmcnt(4)
	v_lshlrev_b32_e32 v114, 16, v114
	s_waitcnt lgkmcnt(3)
	v_lshlrev_b32_e32 v115, 16, v115
	s_waitcnt lgkmcnt(2)
	v_lshlrev_b32_e32 v116, 16, v116
	v_mul_f32_e32 v48, v49, v48
	v_mul_f32_e32 v49, v50, v112
	v_mul_f32_e32 v50, v51, v113
	v_mul_f32_e32 v51, v52, v114
	v_mul_f32_e32 v52, v53, v115
	v_mul_f32_e32 v53, v54, v116
	v_cvt_pk_bf16_f32 v48, v48, s0
	v_cvt_pk_bf16_f32 v49, v49, s0
	v_cvt_pk_bf16_f32 v50, v50, s0
	v_cvt_pk_bf16_f32 v51, v51, s0
	v_cvt_pk_bf16_f32 v52, v52, s0
	v_cvt_pk_bf16_f32 v53, v53, s0
	ds_write_b16 v193, v48
	ds_write_b16 v193, v49 offset:144
	ds_write_b16 v193, v50 offset:288
	ds_write_b16 v193, v51 offset:1008
	ds_write_b16 v193, v52 offset:1152
	ds_write_b16 v193, v53 offset:1296
	ds_read_b128 v[48:51], v185 offset:1536
	v_mul_f32_e32 v119, v138, v127
	v_fmac_f32_e32 v119, v139, v55
	v_add_f32_e32 v52, v131, v119
	s_waitcnt lgkmcnt(8)
	v_lshlrev_b32_e32 v53, 16, v117
	s_waitcnt lgkmcnt(0)
	v_sub_f32_e32 v48, v56, v48
	v_mul_f32_e32 v56, v138, v198
	v_fmac_f32_e32 v56, v139, v48
	s_waitcnt vmcnt(1)
	v_add_f32_e32 v48, v202, v56
	v_lshlrev_b32_e32 v56, 16, v118
	v_mul_f32_e32 v48, v48, v56
	v_mul_f32_e32 v52, v52, v53
	v_cvt_pk_bf16_f32 v48, v48, s0
	v_cvt_pk_bf16_f32 v52, v52, s0
	ds_write_b16 v193, v48 offset:2160
	v_sub_f32_e32 v48, v57, v49
	v_mul_f32_e32 v49, v138, v199
	ds_write_b16 v193, v52 offset:1440
	v_fmac_f32_e32 v49, v139, v48
	ds_read_b128 v[52:55], v186 offset:1024
	v_add_f32_e32 v48, v203, v49
	ds_read_u16 v49, v193 offset:2304
	ds_read_u16 v56, v193 offset:2448
	ds_read_u16 v57, v193 offset:2592
	ds_read_u16 v112, v193 offset:3312
	ds_read_u16 v113, v193 offset:3456
	ds_read_u16 v114, v193 offset:3600
	ds_read_u16 v115, v193 offset:3744
	s_waitcnt lgkmcnt(6)
	v_lshlrev_b32_e32 v49, 16, v49
	v_mul_f32_e32 v48, v48, v49
	v_cvt_pk_bf16_f32 v48, v48, s0
	ds_write_b16 v193, v48 offset:2304
	v_sub_f32_e32 v48, v58, v50
	v_mul_f32_e32 v49, v138, v200
	v_fmac_f32_e32 v49, v139, v48
	v_add_f32_e32 v48, v204, v49
	s_waitcnt lgkmcnt(6)
	v_lshlrev_b32_e32 v49, 16, v56
	v_mul_f32_e32 v48, v48, v49
	v_cvt_pk_bf16_f32 v48, v48, s0
	ds_write_b16 v193, v48 offset:2448
	v_sub_f32_e32 v48, v59, v51
	v_mul_f32_e32 v49, v138, v201
	v_fmac_f32_e32 v49, v139, v48
	v_add_f32_e32 v56, v205, v49
	ds_read_b128 v[48:51], v186 offset:1536
	v_mul_f32_e32 v52, v138, v52
	s_waitcnt lgkmcnt(7)
	v_lshlrev_b32_e32 v57, 16, v57
	v_mul_f32_e32 v56, v56, v57
	v_cvt_pk_bf16_f32 v56, v56, s0
	s_waitcnt lgkmcnt(0)
	v_sub_f32_e32 v48, v60, v48
	v_fmac_f32_e32 v52, v139, v48
	s_waitcnt vmcnt(0)
	v_add_f32_e32 v48, v206, v52
	v_lshlrev_b32_e32 v52, 16, v112
	v_mul_f32_e32 v48, v48, v52
	v_cvt_pk_bf16_f32 v48, v48, s0
	ds_write_b16 v193, v48 offset:3312
	v_sub_f32_e32 v48, v61, v49
	v_mul_f32_e32 v49, v138, v53
	v_fmac_f32_e32 v49, v139, v48
	v_add_f32_e32 v48, v207, v49
	v_lshlrev_b32_e32 v49, 16, v113
	v_mul_f32_e32 v48, v48, v49
	v_cvt_pk_bf16_f32 v48, v48, s0
	ds_write_b16 v193, v48 offset:3456
	v_sub_f32_e32 v48, v62, v50
	v_mul_f32_e32 v49, v138, v54
	v_fmac_f32_e32 v49, v139, v48
	v_add_f32_e32 v48, v208, v49
	v_lshlrev_b32_e32 v49, 16, v114
	v_mul_f32_e32 v48, v48, v49
	v_cvt_pk_bf16_f32 v48, v48, s0
	ds_write_b16 v193, v48 offset:3600
	v_sub_f32_e32 v48, v63, v51
	v_mul_f32_e32 v49, v138, v55
	v_fmac_f32_e32 v49, v139, v48
	v_add_f32_e32 v48, v209, v49
	v_lshlrev_b32_e32 v49, 16, v115
	v_mul_f32_e32 v48, v48, v49
	v_cvt_pk_bf16_f32 v48, v48, s0
	ds_write_b16 v193, v56 offset:2592
	ds_write_b16 v193, v48 offset:3744
	global_load_dwordx4 v[52:55], v[132:133], off offset:128
	v_lshl_add_u64 v[48:49], s[10:11], 0, v[158:159]
	v_lshl_add_u64 v[48:49], v[48:49], 2, s[28:29]
	global_load_dwordx4 v[56:59], v[48:49], off offset:128
	v_mfma_f32_32x32x16_bf16 v[16:31], v[108:111], v[104:107], v[16:31]
	ds_read_b128 v[60:63], v187 offset:1536
	ds_read_b128 v[108:111], v187 offset:1024
	v_lshl_add_u64 v[50:51], s[10:11], 0, v[160:161]
	v_lshl_add_u64 v[50:51], v[50:51], 2, s[28:29]
	s_waitcnt lgkmcnt(1)
	v_sub_f32_e32 v32, v32, v60
	s_waitcnt lgkmcnt(0)
	v_mul_f32_e32 v60, v138, v108
	v_fmac_f32_e32 v60, v139, v32
	v_mfma_f32_32x32x16_bf16 v[0:15], v[100:103], v[104:107], v[0:15]
	global_load_dwordx4 v[100:103], v[50:51], off offset:128
	s_waitcnt vmcnt(2)
	v_add_f32_e32 v32, v52, v60
	ds_read_u16 v52, v183 offset:4608
	ds_read_u16 v60, v183 offset:4752
	ds_read_u16 v104, v183 offset:4896
	ds_read_u16 v105, v183 offset:5040
	ds_read_u16 v108, v183 offset:5760
	ds_read_u16 v112, v183 offset:5904
	ds_read_u16 v113, v183 offset:6048
	ds_read_u16 v114, v183 offset:6192
	s_waitcnt lgkmcnt(7)
	v_lshlrev_b32_e32 v52, 16, v52
	v_mul_f32_e32 v32, v32, v52
	v_cvt_pk_bf16_f32 v32, v32, s0
	ds_write_b16 v183, v32 offset:4608
	v_sub_f32_e32 v32, v33, v61
	v_mul_f32_e32 v33, v138, v109
	v_fmac_f32_e32 v33, v139, v32
	v_add_f32_e32 v32, v53, v33
	s_waitcnt lgkmcnt(7)
	v_lshlrev_b32_e32 v33, 16, v60
	v_mul_f32_e32 v32, v32, v33
	v_cvt_pk_bf16_f32 v32, v32, s0
	ds_write_b16 v183, v32 offset:4752
	v_sub_f32_e32 v32, v34, v62
	v_mul_f32_e32 v33, v138, v110
	v_fmac_f32_e32 v33, v139, v32
	v_add_f32_e32 v32, v54, v33
	s_waitcnt lgkmcnt(7)
	v_lshlrev_b32_e32 v33, 16, v104
	v_mul_f32_e32 v32, v32, v33
	v_cvt_pk_bf16_f32 v32, v32, s0
	ds_write_b16 v183, v32 offset:4896
	v_sub_f32_e32 v32, v35, v63
	v_mul_f32_e32 v33, v138, v111
	v_fmac_f32_e32 v33, v139, v32
	v_add_f32_e32 v32, v55, v33
	s_waitcnt lgkmcnt(7)
	v_lshlrev_b32_e32 v33, 16, v105
	v_mul_f32_e32 v32, v32, v33
	v_cvt_pk_bf16_f32 v32, v32, s0
	ds_write_b16 v183, v32 offset:5040
	v_lshl_add_u64 v[32:33], s[10:11], 0, v[162:163]
	v_lshl_add_u64 v[32:33], v[32:33], 2, s[28:29]
	ds_read_b128 v[52:55], v188 offset:1536
	ds_read_b128 v[60:63], v188 offset:1024
	global_load_dwordx4 v[104:107], v[32:33], off offset:128
	v_mfma_f32_32x32x16_bf16 v[16:31], v[92:95], v[96:99], v[16:31]
	s_waitcnt lgkmcnt(1)
	v_sub_f32_e32 v34, v36, v52
	s_waitcnt lgkmcnt(0)
	v_mul_f32_e32 v35, v138, v60
	v_fmac_f32_e32 v35, v139, v34
	s_waitcnt vmcnt(2)
	v_add_f32_e32 v34, v56, v35
	v_lshlrev_b32_e32 v35, 16, v108
	v_mul_f32_e32 v34, v34, v35
	v_cvt_pk_bf16_f32 v34, v34, s0
	ds_write_b16 v183, v34 offset:5760
	v_sub_f32_e32 v34, v37, v53
	v_mul_f32_e32 v35, v138, v61
	v_fmac_f32_e32 v35, v139, v34
	v_add_f32_e32 v34, v57, v35
	v_lshlrev_b32_e32 v35, 16, v112
	v_mul_f32_e32 v34, v34, v35
	v_cvt_pk_bf16_f32 v34, v34, s0
	ds_write_b16 v183, v34 offset:5904
	v_sub_f32_e32 v34, v38, v54
	v_mul_f32_e32 v35, v138, v62
	v_fmac_f32_e32 v35, v139, v34
	v_add_f32_e32 v34, v58, v35
	v_lshlrev_b32_e32 v35, 16, v113
	v_mul_f32_e32 v34, v34, v35
	v_cvt_pk_bf16_f32 v34, v34, s0
	ds_write_b16 v183, v34 offset:6048
	v_sub_f32_e32 v34, v39, v55
	v_mul_f32_e32 v35, v138, v63
	v_fmac_f32_e32 v35, v139, v34
	v_add_f32_e32 v38, v59, v35
	ds_read_b128 v[34:37], v189 offset:1536
	ds_read_b128 v[52:55], v189 offset:1024
	v_lshlrev_b32_e32 v39, 16, v114
	v_mul_f32_e32 v38, v38, v39
	v_cvt_pk_bf16_f32 v38, v38, s0
	ds_write_b16 v183, v38 offset:6192
	s_waitcnt lgkmcnt(2)
	v_sub_f32_e32 v34, v40, v34
	s_waitcnt lgkmcnt(1)
	v_mul_f32_e32 v38, v138, v52
	v_fmac_f32_e32 v38, v139, v34
	s_waitcnt vmcnt(1)
	v_add_f32_e32 v34, v100, v38
	ds_read_u16 v38, v183 offset:6912
	ds_read_u16 v39, v183 offset:7056
	ds_read_u16 v40, v183 offset:7200
	ds_read_u16 v52, v183 offset:7344
	ds_read_u16 v56, v183 offset:8064
	ds_read_u16 v57, v183 offset:8208
	ds_read_u16 v58, v183 offset:8352
	ds_read_u16 v59, v183 offset:8496
	s_waitcnt lgkmcnt(7)
	v_lshlrev_b32_e32 v38, 16, v38
	v_mul_f32_e32 v34, v34, v38
	v_cvt_pk_bf16_f32 v34, v34, s0
	ds_write_b16 v183, v34 offset:6912
	v_sub_f32_e32 v34, v41, v35
	v_mul_f32_e32 v35, v138, v53
	v_fmac_f32_e32 v35, v139, v34
	v_add_f32_e32 v34, v101, v35
	s_waitcnt lgkmcnt(7)
	v_lshlrev_b32_e32 v35, 16, v39
	v_mul_f32_e32 v34, v34, v35
	v_cvt_pk_bf16_f32 v34, v34, s0
	ds_write_b16 v183, v34 offset:7056
	v_sub_f32_e32 v34, v42, v36
	v_mul_f32_e32 v35, v138, v54
	v_fmac_f32_e32 v35, v139, v34
	v_add_f32_e32 v34, v102, v35
	s_waitcnt lgkmcnt(7)
	v_lshlrev_b32_e32 v35, 16, v40
	v_mul_f32_e32 v34, v34, v35
	v_cvt_pk_bf16_f32 v34, v34, s0
	ds_write_b16 v183, v34 offset:7200
	v_sub_f32_e32 v34, v43, v37
	v_mul_f32_e32 v35, v138, v55
	v_fmac_f32_e32 v35, v139, v34
	v_add_f32_e32 v42, v103, v35
	ds_read_b128 v[34:37], v190 offset:1536
	ds_read_b128 v[38:41], v190 offset:1024
	s_waitcnt lgkmcnt(9)
	v_lshlrev_b32_e32 v43, 16, v52
	v_mul_f32_e32 v42, v42, v43
	v_cvt_pk_bf16_f32 v42, v42, s0
	s_waitcnt lgkmcnt(1)
	v_sub_f32_e32 v34, v44, v34
	s_waitcnt lgkmcnt(0)
	v_mul_f32_e32 v38, v138, v38
	v_fmac_f32_e32 v38, v139, v34
	ds_write_b16 v183, v42 offset:7344
	v_mfma_f32_32x32x16_bf16 v[16:31], v[84:87], v[76:79], v[16:31]
	s_waitcnt vmcnt(0)
	v_add_f32_e32 v34, v104, v38
	v_lshlrev_b32_e32 v38, 16, v56
	v_mul_f32_e32 v34, v34, v38
	v_cvt_pk_bf16_f32 v34, v34, s0
	ds_write_b16 v183, v34 offset:8064
	v_sub_f32_e32 v34, v45, v35
	v_mul_f32_e32 v35, v138, v39
	v_fmac_f32_e32 v35, v139, v34
	v_add_f32_e32 v34, v105, v35
	v_lshlrev_b32_e32 v35, 16, v57
	v_mul_f32_e32 v34, v34, v35
	v_cvt_pk_bf16_f32 v34, v34, s0
	ds_write_b16 v183, v34 offset:8208
	v_sub_f32_e32 v34, v46, v36
	v_mul_f32_e32 v35, v138, v40
	v_fmac_f32_e32 v35, v139, v34
	v_add_f32_e32 v34, v106, v35
	v_lshlrev_b32_e32 v35, 16, v58
	v_mul_f32_e32 v34, v34, v35
	v_cvt_pk_bf16_f32 v34, v34, s0
	ds_write_b16 v183, v34 offset:8352
	v_sub_f32_e32 v34, v47, v37
	v_mul_f32_e32 v35, v138, v41
	v_fmac_f32_e32 v35, v139, v34
	v_add_f32_e32 v34, v107, v35
	v_lshlrev_b32_e32 v35, 16, v59
	v_mul_f32_e32 v34, v34, v35
	v_cvt_pk_bf16_f32 v34, v34, s0
	ds_write_b16 v183, v34 offset:8496
	global_load_dword v34, v[170:171], off offset:128
	global_load_dword v35, v[136:137], off offset:128
	global_load_dword v56, v[134:135], off
	global_load_dwordx3 v[60:62], v[132:133], off offset:4
	global_load_dwordx4 v[36:39], v[132:133], off offset:32
	v_mfma_f32_32x32x16_bf16 v[16:31], v[80:83], v[68:71], v[16:31]
	ds_read_b128 v[40:43], v182 offset:1536
	ds_read_b128 v[44:47], v182 offset:1024
	global_load_dwordx4 v[52:55], v[132:133], off offset:64
	v_mfma_f32_32x32x16_bf16 v[0:15], v[88:91], v[96:99], v[0:15]
	s_waitcnt lgkmcnt(1)
	s_nop 6
	v_sub_f32_e32 v16, v16, v40
	s_waitcnt vmcnt(5) lgkmcnt(0)
	v_mul_f32_e32 v40, v34, v44
	ds_read_u16 v44, v183 offset:64
	s_waitcnt vmcnt(4)
	v_fmac_f32_e32 v40, v35, v16
	s_waitcnt vmcnt(3)
	v_add_f32_e32 v16, v56, v40
	ds_read_b128 v[56:59], v184 offset:1024
	v_mfma_f32_32x32x16_bf16 v[0:15], v[72:75], v[76:79], v[0:15]
	s_waitcnt lgkmcnt(1)
	v_lshlrev_b32_e32 v40, 16, v44
	v_mul_f32_e32 v16, v16, v40
	v_cvt_pk_bf16_f32 v16, v16, s0
	ds_write_b16 v183, v16 offset:64
	v_sub_f32_e32 v16, v17, v41
	v_mul_f32_e32 v16, v35, v16
	v_fmac_f32_e32 v16, v34, v45
	s_waitcnt vmcnt(2)
	v_add_f32_e32 v16, v60, v16
	ds_read_u16 v17, v193 offset:64
	ds_read_u16 v40, v193 offset:208
	ds_read_u16 v41, v193 offset:352
	ds_read_u16 v60, v193 offset:1072
	ds_read_u16 v63, v193 offset:1216
	ds_read_u16 v80, v193 offset:1360
	ds_read_u16 v81, v193 offset:1504
	ds_read_u16 v82, v193 offset:2224
	s_waitcnt lgkmcnt(7)
	v_lshlrev_b32_e32 v17, 16, v17
	v_mul_f32_e32 v16, v16, v17
	v_cvt_pk_bf16_f32 v16, v16, s0
	ds_write_b16 v193, v16 offset:64
	v_sub_f32_e32 v16, v18, v42
	v_mul_f32_e32 v16, v35, v16
	v_fmac_f32_e32 v16, v34, v46
	v_add_f32_e32 v16, v61, v16
	s_waitcnt lgkmcnt(7)
	v_lshlrev_b32_e32 v17, 16, v40
	v_mul_f32_e32 v16, v16, v17
	v_cvt_pk_bf16_f32 v16, v16, s0
	ds_write_b16 v193, v16 offset:208
	v_sub_f32_e32 v16, v19, v43
	v_mul_f32_e32 v16, v35, v16
	v_fmac_f32_e32 v16, v34, v47
	v_add_f32_e32 v16, v62, v16
	s_waitcnt lgkmcnt(7)
	v_lshlrev_b32_e32 v17, 16, v41
	v_mul_f32_e32 v40, v16, v17
	v_cvt_pk_bf16_f32 v44, v40, s0
	global_load_dwordx4 v[40:43], v[132:133], off offset:96
	ds_read_b128 v[16:19], v184 offset:1536
	ds_write_b16 v193, v44 offset:352
	ds_read_b128 v[44:47], v185 offset:1024
	v_mfma_f32_32x32x16_bf16 v[0:15], v[64:67], v[68:71], v[0:15]
	s_waitcnt lgkmcnt(2)
	v_sub_f32_e32 v16, v20, v16
	v_mul_f32_e32 v16, v35, v16
	v_fmac_f32_e32 v16, v34, v56
	s_waitcnt vmcnt(2)
	v_add_f32_e32 v16, v36, v16
	v_lshlrev_b32_e32 v20, 16, v60
	v_mul_f32_e32 v16, v16, v20
	v_cvt_pk_bf16_f32 v16, v16, s0
	ds_write_b16 v193, v16 offset:1072
	v_sub_f32_e32 v16, v21, v17
	v_mul_f32_e32 v16, v35, v16
	v_fmac_f32_e32 v16, v34, v57
	v_add_f32_e32 v16, v37, v16
	v_lshlrev_b32_e32 v17, 16, v63
	v_mul_f32_e32 v16, v16, v17
	v_cvt_pk_bf16_f32 v16, v16, s0
	ds_write_b16 v193, v16 offset:1216
	v_sub_f32_e32 v16, v22, v18
	v_mul_f32_e32 v16, v35, v16
	v_fmac_f32_e32 v16, v34, v58
	v_add_f32_e32 v16, v38, v16
	v_lshlrev_b32_e32 v17, 16, v80
	v_mul_f32_e32 v16, v16, v17
	v_cvt_pk_bf16_f32 v16, v16, s0
	ds_write_b16 v193, v16 offset:1360
	v_sub_f32_e32 v16, v23, v19
	v_mul_f32_e32 v16, v35, v16
	v_fmac_f32_e32 v16, v34, v59
	v_add_f32_e32 v20, v39, v16
	ds_read_b128 v[16:19], v185 offset:1536
	v_lshlrev_b32_e32 v21, 16, v81
	v_mul_f32_e32 v20, v20, v21
	v_cvt_pk_bf16_f32 v20, v20, s0
	ds_write_b16 v193, v20 offset:1504
	s_waitcnt lgkmcnt(1)
	v_sub_f32_e32 v16, v24, v16
	v_mul_f32_e32 v16, v35, v16
	v_fmac_f32_e32 v16, v34, v44
	s_waitcnt vmcnt(1)
	v_add_f32_e32 v16, v52, v16
	v_lshlrev_b32_e32 v24, 16, v82
	v_mul_f32_e32 v16, v16, v24
	v_cvt_pk_bf16_f32 v16, v16, s0
	ds_write_b16 v193, v16 offset:2224
	v_sub_f32_e32 v16, v25, v17
	v_mul_f32_e32 v16, v35, v16
	ds_read_b128 v[20:23], v186 offset:1024
	v_fmac_f32_e32 v16, v34, v45
	ds_read_u16 v17, v193 offset:2368
	ds_read_u16 v24, v193 offset:2512
	ds_read_u16 v25, v193 offset:2656
	ds_read_u16 v36, v193 offset:3376
	ds_read_u16 v37, v193 offset:3520
	ds_read_u16 v38, v193 offset:3664
	ds_read_u16 v39, v193 offset:3808
	v_add_f32_e32 v16, v53, v16
	s_waitcnt lgkmcnt(6)
	v_lshlrev_b32_e32 v17, 16, v17
	v_mul_f32_e32 v16, v16, v17
	v_cvt_pk_bf16_f32 v16, v16, s0
	ds_write_b16 v193, v16 offset:2368
	v_sub_f32_e32 v16, v26, v18
	v_mul_f32_e32 v16, v35, v16
	v_fmac_f32_e32 v16, v34, v46
	v_add_f32_e32 v16, v54, v16
	s_waitcnt lgkmcnt(6)
	v_lshlrev_b32_e32 v17, 16, v24
	v_mul_f32_e32 v16, v16, v17
	v_cvt_pk_bf16_f32 v16, v16, s0
	ds_write_b16 v193, v16 offset:2512
	v_sub_f32_e32 v16, v27, v19
	v_mul_f32_e32 v16, v35, v16
	v_fmac_f32_e32 v16, v34, v47
	v_add_f32_e32 v24, v55, v16
	ds_read_b128 v[16:19], v186 offset:1536
	s_waitcnt lgkmcnt(7)
	v_lshlrev_b32_e32 v25, 16, v25
	v_mul_f32_e32 v24, v24, v25
	v_cvt_pk_bf16_f32 v24, v24, s0
	ds_write_b16 v193, v24 offset:2656
	s_waitcnt lgkmcnt(1)
	v_sub_f32_e32 v16, v28, v16
	v_mul_f32_e32 v16, v35, v16
	v_fmac_f32_e32 v16, v34, v20
	v_lshlrev_b32_e32 v20, 16, v36
	s_waitcnt vmcnt(0)
	v_add_f32_e32 v16, v40, v16
	v_mul_f32_e32 v16, v16, v20
	v_cvt_pk_bf16_f32 v16, v16, s0
	ds_write_b16 v193, v16 offset:3376
	v_sub_f32_e32 v16, v29, v17
	v_mul_f32_e32 v16, v35, v16
	v_fmac_f32_e32 v16, v34, v21
	v_add_f32_e32 v16, v41, v16
	v_lshlrev_b32_e32 v17, 16, v37
	v_mul_f32_e32 v16, v16, v17
	v_cvt_pk_bf16_f32 v16, v16, s0
	ds_write_b16 v193, v16 offset:3520
	v_sub_f32_e32 v16, v30, v18
	v_mul_f32_e32 v16, v35, v16
	v_fmac_f32_e32 v16, v34, v22
	v_add_f32_e32 v16, v42, v16
	v_lshlrev_b32_e32 v17, 16, v38
	v_mul_f32_e32 v16, v16, v17
	v_cvt_pk_bf16_f32 v16, v16, s0
	ds_write_b16 v193, v16 offset:3664
	v_sub_f32_e32 v16, v31, v19
	v_mul_f32_e32 v16, v35, v16
	v_fmac_f32_e32 v16, v34, v23
	v_add_f32_e32 v16, v43, v16
	v_lshlrev_b32_e32 v17, 16, v39
	v_mul_f32_e32 v16, v16, v17
	v_cvt_pk_bf16_f32 v16, v16, s0
	ds_write_b16 v193, v16 offset:3808
	global_load_dwordx4 v[16:19], v[132:133], off offset:128
	global_load_dwordx4 v[20:23], v[48:49], off offset:128
	ds_read_b128 v[24:27], v187 offset:1536
	ds_read_b128 v[28:31], v187 offset:1024
	global_load_dwordx4 v[36:39], v[50:51], off offset:128
	s_waitcnt lgkmcnt(1)
	v_sub_f32_e32 v0, v0, v24
	s_waitcnt lgkmcnt(0)
	v_mul_f32_e32 v24, v34, v28
	v_fmac_f32_e32 v24, v35, v0
	s_waitcnt vmcnt(2)
	v_add_f32_e32 v0, v16, v24
	ds_read_u16 v16, v183 offset:4672
	ds_read_u16 v24, v183 offset:4816
	ds_read_u16 v28, v183 offset:4960
	ds_read_u16 v40, v183 offset:5104
	ds_read_u16 v41, v183 offset:5824
	ds_read_u16 v42, v183 offset:5968
	ds_read_u16 v43, v183 offset:6112
	ds_read_u16 v44, v183 offset:6256
	s_waitcnt lgkmcnt(7)
	v_lshlrev_b32_e32 v16, 16, v16
	v_mul_f32_e32 v0, v0, v16
	v_cvt_pk_bf16_f32 v0, v0, s0
	ds_write_b16 v183, v0 offset:4672
	v_sub_f32_e32 v0, v1, v25
	v_mul_f32_e32 v0, v35, v0
	v_fmac_f32_e32 v0, v34, v29
	v_add_f32_e32 v0, v17, v0
	s_waitcnt lgkmcnt(7)
	v_lshlrev_b32_e32 v1, 16, v24
	v_mul_f32_e32 v0, v0, v1
	v_cvt_pk_bf16_f32 v0, v0, s0
	ds_write_b16 v183, v0 offset:4816
	v_sub_f32_e32 v0, v2, v26
	v_mul_f32_e32 v0, v35, v0
	v_fmac_f32_e32 v0, v34, v30
	v_add_f32_e32 v0, v18, v0
	s_waitcnt lgkmcnt(7)
	v_lshlrev_b32_e32 v1, 16, v28
	v_mul_f32_e32 v0, v0, v1
	v_cvt_pk_bf16_f32 v0, v0, s0
	ds_write_b16 v183, v0 offset:4960
	v_sub_f32_e32 v0, v3, v27
	v_mul_f32_e32 v0, v35, v0
	v_fmac_f32_e32 v0, v34, v31
	v_add_f32_e32 v24, v19, v0
	s_waitcnt lgkmcnt(7)
	v_lshlrev_b32_e32 v25, 16, v40
	v_mul_f32_e32 v24, v24, v25
	v_cvt_pk_bf16_f32 v24, v24, s0
	ds_read_b128 v[0:3], v188 offset:1024
	ds_read_b128 v[16:19], v188 offset:1536
	ds_write_b16 v183, v24 offset:5104
	global_load_dwordx4 v[24:27], v[32:33], off offset:128
	s_waitcnt lgkmcnt(1)
	v_sub_f32_e32 v4, v4, v16
	v_mul_f32_e32 v4, v35, v4
	v_fmac_f32_e32 v4, v34, v0
	s_waitcnt vmcnt(2)
	v_add_f32_e32 v0, v20, v4
	v_lshlrev_b32_e32 v4, 16, v41
	v_mul_f32_e32 v0, v0, v4
	v_cvt_pk_bf16_f32 v0, v0, s0
	ds_write_b16 v183, v0 offset:5824
	v_sub_f32_e32 v0, v5, v17
	v_mul_f32_e32 v0, v35, v0
	v_fmac_f32_e32 v0, v34, v1
	v_add_f32_e32 v0, v21, v0
	v_lshlrev_b32_e32 v1, 16, v42
	v_mul_f32_e32 v0, v0, v1
	v_cvt_pk_bf16_f32 v0, v0, s0
	ds_write_b16 v183, v0 offset:5968
	v_sub_f32_e32 v0, v6, v18
	v_mul_f32_e32 v0, v35, v0
	v_fmac_f32_e32 v0, v34, v2
	v_add_f32_e32 v0, v22, v0
	v_lshlrev_b32_e32 v1, 16, v43
	v_mul_f32_e32 v0, v0, v1
	v_cvt_pk_bf16_f32 v0, v0, s0
	ds_write_b16 v183, v0 offset:6112
	v_sub_f32_e32 v0, v7, v19
	v_mul_f32_e32 v0, v35, v0
	v_fmac_f32_e32 v0, v34, v3
	v_add_f32_e32 v16, v23, v0
	ds_read_b128 v[0:3], v189 offset:1024
	ds_read_b128 v[4:7], v189 offset:1536
	v_lshlrev_b32_e32 v17, 16, v44
	v_mul_f32_e32 v16, v16, v17
	v_cvt_pk_bf16_f32 v16, v16, s0
	ds_write_b16 v183, v16 offset:6256
	s_waitcnt lgkmcnt(1)
	v_sub_f32_e32 v4, v8, v4
	v_mul_f32_e32 v4, v35, v4
	v_fmac_f32_e32 v4, v34, v0
	s_waitcnt vmcnt(1)
	v_add_f32_e32 v0, v36, v4
	ds_read_u16 v4, v183 offset:6976
	ds_read_u16 v8, v183 offset:7120
	ds_read_u16 v16, v183 offset:7264
	ds_read_u16 v17, v183 offset:7408
	ds_read_u16 v18, v183 offset:8128
	ds_read_u16 v19, v183 offset:8272
	ds_read_u16 v20, v183 offset:8416
	ds_read_u16 v21, v183 offset:8560
	s_waitcnt lgkmcnt(7)
	v_lshlrev_b32_e32 v4, 16, v4
	v_mul_f32_e32 v0, v0, v4
	v_cvt_pk_bf16_f32 v0, v0, s0
	ds_write_b16 v183, v0 offset:6976
	v_sub_f32_e32 v0, v9, v5
	v_mul_f32_e32 v0, v35, v0
	v_fmac_f32_e32 v0, v34, v1
	v_add_f32_e32 v0, v37, v0
	s_waitcnt lgkmcnt(7)
	v_lshlrev_b32_e32 v1, 16, v8
	v_mul_f32_e32 v0, v0, v1
	v_cvt_pk_bf16_f32 v0, v0, s0
	ds_write_b16 v183, v0 offset:7120
	v_sub_f32_e32 v0, v10, v6
	v_mul_f32_e32 v0, v35, v0
	v_fmac_f32_e32 v0, v34, v2
	v_add_f32_e32 v0, v38, v0
	s_waitcnt lgkmcnt(7)
	v_lshlrev_b32_e32 v1, 16, v16
	v_mul_f32_e32 v0, v0, v1
	v_cvt_pk_bf16_f32 v0, v0, s0
	ds_write_b16 v183, v0 offset:7264
	v_sub_f32_e32 v0, v11, v7
	v_mul_f32_e32 v0, v35, v0
	v_fmac_f32_e32 v0, v34, v3
	v_add_f32_e32 v8, v39, v0
	ds_read_b128 v[0:3], v190 offset:1024
	ds_read_b128 v[4:7], v190 offset:1536
	s_waitcnt lgkmcnt(9)
	v_lshlrev_b32_e32 v9, 16, v17
	v_mul_f32_e32 v8, v8, v9
	v_cvt_pk_bf16_f32 v8, v8, s0
	ds_write_b16 v183, v8 offset:7408
	s_waitcnt lgkmcnt(1)
	v_sub_f32_e32 v4, v12, v4
	v_mul_f32_e32 v4, v35, v4
	v_fmac_f32_e32 v4, v34, v0
	s_waitcnt vmcnt(0)
	v_add_f32_e32 v0, v24, v4
	v_lshlrev_b32_e32 v4, 16, v18
	v_mul_f32_e32 v0, v0, v4
	v_cvt_pk_bf16_f32 v0, v0, s0
	ds_write_b16 v183, v0 offset:8128
	v_sub_f32_e32 v0, v13, v5
	v_mul_f32_e32 v0, v35, v0
	v_fmac_f32_e32 v0, v34, v1
	v_add_f32_e32 v0, v25, v0
	v_lshlrev_b32_e32 v1, 16, v19
	v_mul_f32_e32 v0, v0, v1
	v_cvt_pk_bf16_f32 v0, v0, s0
	ds_write_b16 v183, v0 offset:8272
	v_sub_f32_e32 v0, v14, v6
	v_mul_f32_e32 v0, v35, v0
	v_fmac_f32_e32 v0, v34, v2
	v_add_f32_e32 v0, v26, v0
	v_lshlrev_b32_e32 v1, 16, v20
	v_mul_f32_e32 v0, v0, v1
	v_cvt_pk_bf16_f32 v0, v0, s0
	ds_write_b16 v183, v0 offset:8416
	v_sub_f32_e32 v0, v15, v7
	v_mul_f32_e32 v0, v35, v0
	v_fmac_f32_e32 v0, v34, v3
	v_add_f32_e32 v0, v27, v0
	v_lshlrev_b32_e32 v1, 16, v21
	v_mul_f32_e32 v0, v0, v1
	v_cvt_pk_bf16_f32 v0, v0, s0
	ds_write_b16 v183, v0 offset:8560
	s_waitcnt lgkmcnt(0)
	v_mov_b32_e32 v0, v192
